# hyena conv d-loop: next-iteration address updates and LDS reads interleaved one per MFMA gap (on top of the conflict-free LDS layout)
# baseline (speedup 1.0000x reference)
; #define MFMA16(a, b, c) __builtin_amdgcn_mfma_f32_16x16x32_bf16(__builtin_bit_cast(bf16x8, (a)), __builtin_bit_cast(bf16x8, (b)), (c), 0, 0, 0)
; DI void hyena_conv_unit(const Params& p, int item, char* smem) {
;     ...
;   auto bfrag = [&](int E) -> u32x4 {
;     int a = 4095 - 16 * E - n + 8 * g;
;     const bf16_t* src = (a & 1) ? (sG1 + (a - 1)) : (sG0 + a);
;     const unsigned* s32 = (const unsigned*)src;
;     u32x4 o = {s32[0], s32[1], s32[2], s32[3]};
;     return o;
;   };
;   for (int d = -63; d <= 63; ++d) {
; #pragma unroll
;     for (int kk = 0; kk < 2; ++kk) {
;       u32x4 bfr[4];
; #pragma unroll
;       for (int nn = 0; nn < 4; ++nn) bfr[nn] = bfrag(4 * d + nn - 2 * kk);
; #pragma unroll
;       for (int rb = 0; rb < 4; ++rb) {
;         if (d >= 16 * rb - 63 && d <= 16 * rb + 15) {
;           int t1 = 16 * rb + n, s1 = t1 - d;
;           u32x4 a = zero4();
;           if (s1 >= 0 && s1 < 64) a = *(const u32x4*)(su + s1 * 72 + 32 * kk + 8 * g);
; #pragma unroll
;           for (int nn = 0; nn < 4; ++nn) acc[rb][nn] = MFMA16(a, bfr[nn], acc[rb][nn]);
;         }
;       }
;     }
;   }
.Lconv_seg0:
	s_waitcnt lgkmcnt(0)
	v_mfma_f32_16x16x32_bf16 v[64:67], v[132:135], v[180:183], v[64:67]
	v_add_u32_e32 v95, -1, v95
	v_add_u32_e32 v72, 0xffffffd0, v95
	v_cmp_gt_u32_e64 s[0:1], 64, v72
	v_mfma_f32_16x16x32_bf16 v[60:63], v[132:135], v[184:187], v[60:63]
	v_add_u32_e32 v97, 0xffffff80, v97
	ds_read2_b32 v[164:165], v97 offset0:24 offset1:25
	ds_read2_b32 v[166:167], v97 offset0:26 offset1:27
	v_mfma_f32_16x16x32_bf16 v[64:67], v[136:139], v[172:175], v[64:67]
	ds_read2_b32 v[168:169], v97 offset0:16 offset1:17
	ds_read2_b32 v[170:171], v97 offset0:18 offset1:19
	v_add_u32_e32 v96, 0xffffff60, v96
	v_mfma_f32_16x16x32_bf16 v[60:63], v[136:139], v[176:179], v[60:63]
	v_cndmask_b32_e64 v76, v68, v96, s[0:1]
	ds_read_b128 v[100:103], v76 offset:0
	ds_read_b128 v[104:107], v76 offset:64
	v_mfma_f32_16x16x32_bf16 v[56:59], v[132:135], v[188:191], v[56:59]
	ds_read2_b32 v[172:173], v97 offset0:8 offset1:9
	ds_read2_b32 v[174:175], v97 offset0:10 offset1:11
	ds_read2_b32 v[176:177], v97 offset0:0 offset1:1
	v_mfma_f32_16x16x32_bf16 v[52:55], v[132:135], v[192:195], v[52:55]
	ds_read2_b32 v[178:179], v97 offset0:2 offset1:3
	v_mfma_f32_16x16x32_bf16 v[56:59], v[136:139], v[180:183], v[56:59]
	v_mfma_f32_16x16x32_bf16 v[52:55], v[136:139], v[184:187], v[52:55]
	s_waitcnt lgkmcnt(0)
	v_mfma_f32_16x16x32_bf16 v[64:67], v[100:103], v[164:167], v[64:67]
	v_add_u32_e32 v95, -1, v95
	v_add_u32_e32 v72, 0xffffffd0, v95
	v_cmp_gt_u32_e64 s[0:1], 64, v72
	v_mfma_f32_16x16x32_bf16 v[60:63], v[100:103], v[168:171], v[60:63]
	v_add_u32_e32 v97, 0xffffff80, v97
	ds_read2_b32 v[180:181], v97 offset0:24 offset1:25
	ds_read2_b32 v[182:183], v97 offset0:26 offset1:27
	v_mfma_f32_16x16x32_bf16 v[64:67], v[104:107], v[188:191], v[64:67]
	ds_read2_b32 v[184:185], v97 offset0:16 offset1:17
	ds_read2_b32 v[186:187], v97 offset0:18 offset1:19
	v_add_u32_e32 v96, 0xffffff60, v96
	v_mfma_f32_16x16x32_bf16 v[60:63], v[104:107], v[192:195], v[60:63]
	v_cndmask_b32_e64 v76, v68, v96, s[0:1]
	ds_read_b128 v[132:135], v76 offset:0
	ds_read_b128 v[136:139], v76 offset:64
	v_mfma_f32_16x16x32_bf16 v[56:59], v[100:103], v[172:175], v[56:59]
	ds_read2_b32 v[188:189], v97 offset0:8 offset1:9
	ds_read2_b32 v[190:191], v97 offset0:10 offset1:11
	ds_read2_b32 v[192:193], v97 offset0:0 offset1:1
	v_mfma_f32_16x16x32_bf16 v[52:55], v[100:103], v[176:179], v[52:55]
	ds_read2_b32 v[194:195], v97 offset0:2 offset1:3
	v_mfma_f32_16x16x32_bf16 v[56:59], v[104:107], v[164:167], v[56:59]
	v_mfma_f32_16x16x32_bf16 v[52:55], v[104:107], v[168:171], v[52:55]
	s_sub_u32 s24, s24, 1
	s_cmp_lg_u32 s24, 0
	s_cbranch_scc1 .Lconv_seg0
	s_waitcnt lgkmcnt(0)
	v_mfma_f32_16x16x32_bf16 v[64:67], v[132:135], v[180:183], v[64:67]
	v_add_u32_e32 v95, -1, v95
	v_add_u32_e32 v72, 0xffffffd0, v95
	v_cmp_gt_u32_e64 s[0:1], 64, v72
	v_mfma_f32_16x16x32_bf16 v[60:63], v[132:135], v[184:187], v[60:63]
	v_add_u32_e32 v97, 0xffffff80, v97
	ds_read2_b32 v[164:165], v97 offset0:24 offset1:25
	ds_read2_b32 v[166:167], v97 offset0:26 offset1:27
	v_mfma_f32_16x16x32_bf16 v[64:67], v[136:139], v[172:175], v[64:67]
	ds_read2_b32 v[168:169], v97 offset0:16 offset1:17
	ds_read2_b32 v[170:171], v97 offset0:18 offset1:19
	v_add_u32_e32 v96, 0xffffff60, v96
	v_mfma_f32_16x16x32_bf16 v[60:63], v[136:139], v[176:179], v[60:63]
	v_cndmask_b32_e64 v76, v68, v96, s[0:1]
	ds_read_b128 v[100:103], v76 offset:0
	ds_read_b128 v[104:107], v76 offset:64
	v_mfma_f32_16x16x32_bf16 v[56:59], v[132:135], v[188:191], v[56:59]
	ds_read2_b32 v[172:173], v97 offset0:8 offset1:9
	ds_read2_b32 v[174:175], v97 offset0:10 offset1:11
	ds_read2_b32 v[176:177], v97 offset0:0 offset1:1
	v_mfma_f32_16x16x32_bf16 v[52:55], v[132:135], v[192:195], v[52:55]
	ds_read2_b32 v[178:179], v97 offset0:2 offset1:3
	v_mfma_f32_16x16x32_bf16 v[56:59], v[136:139], v[180:183], v[56:59]
	v_mfma_f32_16x16x32_bf16 v[52:55], v[136:139], v[184:187], v[52:55]
	s_waitcnt lgkmcnt(0)
	v_mfma_f32_16x16x32_bf16 v[64:67], v[100:103], v[164:167], v[64:67]
	v_add_u32_e32 v95, -1, v95
	v_add_u32_e32 v72, 0xffffffd0, v95
	v_cmp_gt_u32_e64 s[0:1], 64, v72
	v_add_u32_e32 v73, 0xffffffe0, v95
	v_mfma_f32_16x16x32_bf16 v[60:63], v[100:103], v[168:171], v[60:63]
	v_cmp_gt_u32_e64 s[4:5], 64, v73
	v_add_u32_e32 v97, 0xffffff80, v97
	ds_read2_b32 v[180:181], v97 offset0:24 offset1:25
	ds_read2_b32 v[182:183], v97 offset0:26 offset1:27
	v_mfma_f32_16x16x32_bf16 v[64:67], v[104:107], v[188:191], v[64:67]
	ds_read2_b32 v[184:185], v97 offset0:16 offset1:17
	ds_read2_b32 v[186:187], v97 offset0:18 offset1:19
	v_add_u32_e32 v96, 0xffffff60, v96
	v_cndmask_b32_e64 v76, v68, v96, s[0:1]
	v_mfma_f32_16x16x32_bf16 v[60:63], v[104:107], v[192:195], v[60:63]
	ds_read_b128 v[132:135], v76 offset:0
	ds_read_b128 v[136:139], v76 offset:64
	v_cndmask_b32_e64 v77, v69, v96, s[4:5]
	ds_read_b128 v[140:143], v77 offset:2560
	v_mfma_f32_16x16x32_bf16 v[56:59], v[100:103], v[172:175], v[56:59]
	ds_read_b128 v[144:147], v77 offset:2624
	ds_read2_b32 v[188:189], v97 offset0:8 offset1:9
	ds_read2_b32 v[190:191], v97 offset0:10 offset1:11
	ds_read2_b32 v[192:193], v97 offset0:0 offset1:1
	v_mfma_f32_16x16x32_bf16 v[52:55], v[100:103], v[176:179], v[52:55]
	ds_read2_b32 v[194:195], v97 offset0:2 offset1:3
	v_mfma_f32_16x16x32_bf16 v[56:59], v[104:107], v[164:167], v[56:59]
	v_mfma_f32_16x16x32_bf16 v[52:55], v[104:107], v[168:171], v[52:55]
	s_mov_b32 s24, 7
; #define MFMA16(a, b, c) __builtin_amdgcn_mfma_f32_16x16x32_bf16(__builtin_bit_cast(bf16x8, (a)), __builtin_bit_cast(bf16x8, (b)), (c), 0, 0, 0)
; DI void hyena_conv_unit(const Params& p, int item, char* smem) {
;     ...
;   auto bfrag = [&](int E) -> u32x4 {
;     int a = 4095 - 16 * E - n + 8 * g;
;     const bf16_t* src = (a & 1) ? (sG1 + (a - 1)) : (sG0 + a);
;     const unsigned* s32 = (const unsigned*)src;
;     u32x4 o = {s32[0], s32[1], s32[2], s32[3]};
;     return o;
;   };
;   for (int d = -63; d <= 63; ++d) {
; #pragma unroll
;     for (int kk = 0; kk < 2; ++kk) {
;       u32x4 bfr[4];
; #pragma unroll
;       for (int nn = 0; nn < 4; ++nn) bfr[nn] = bfrag(4 * d + nn - 2 * kk);
; #pragma unroll
;       for (int rb = 0; rb < 4; ++rb) {
;         if (d >= 16 * rb - 63 && d <= 16 * rb + 15) {
;           int t1 = 16 * rb + n, s1 = t1 - d;
;           u32x4 a = zero4();
;           if (s1 >= 0 && s1 < 64) a = *(const u32x4*)(su + s1 * 72 + 32 * kk + 8 * g);
; #pragma unroll
;           for (int nn = 0; nn < 4; ++nn) acc[rb][nn] = MFMA16(a, bfr[nn], acc[rb][nn]);
;         }
;       }
;     }
;   }
.Lconv_seg1:
	s_waitcnt lgkmcnt(0)
	v_mfma_f32_16x16x32_bf16 v[64:67], v[132:135], v[180:183], v[64:67]
	v_add_u32_e32 v95, -1, v95
	v_add_u32_e32 v72, 0xffffffd0, v95
	v_mfma_f32_16x16x32_bf16 v[60:63], v[132:135], v[184:187], v[60:63]
	v_cmp_gt_u32_e64 s[0:1], 64, v72
	v_add_u32_e32 v73, 0xffffffe0, v95
	v_mfma_f32_16x16x32_bf16 v[64:67], v[136:139], v[172:175], v[64:67]
	v_cmp_gt_u32_e64 s[4:5], 64, v73
	v_add_u32_e32 v97, 0xffffff80, v97
	v_mfma_f32_16x16x32_bf16 v[60:63], v[136:139], v[176:179], v[60:63]
	ds_read2_b32 v[164:165], v97 offset0:24 offset1:25
	ds_read2_b32 v[166:167], v97 offset0:26 offset1:27
	v_mfma_f32_16x16x32_bf16 v[48:51], v[140:143], v[180:183], v[48:51]
	ds_read2_b32 v[168:169], v97 offset0:16 offset1:17
	ds_read2_b32 v[170:171], v97 offset0:18 offset1:19
	v_mfma_f32_16x16x32_bf16 v[44:47], v[140:143], v[184:187], v[44:47]
	v_add_u32_e32 v96, 0xffffff60, v96
	v_cndmask_b32_e64 v76, v68, v96, s[0:1]
	v_mfma_f32_16x16x32_bf16 v[48:51], v[144:147], v[172:175], v[48:51]
	ds_read_b128 v[100:103], v76 offset:0
	ds_read_b128 v[104:107], v76 offset:64
	v_mfma_f32_16x16x32_bf16 v[44:47], v[144:147], v[176:179], v[44:47]
	v_cndmask_b32_e64 v77, v69, v96, s[4:5]
	ds_read_b128 v[108:111], v77 offset:2560
	v_mfma_f32_16x16x32_bf16 v[56:59], v[132:135], v[188:191], v[56:59]
	ds_read_b128 v[112:115], v77 offset:2624
	ds_read2_b32 v[172:173], v97 offset0:8 offset1:9
	v_mfma_f32_16x16x32_bf16 v[52:55], v[132:135], v[192:195], v[52:55]
	ds_read2_b32 v[174:175], v97 offset0:10 offset1:11
	ds_read2_b32 v[176:177], v97 offset0:0 offset1:1
	v_mfma_f32_16x16x32_bf16 v[56:59], v[136:139], v[180:183], v[56:59]
	ds_read2_b32 v[178:179], v97 offset0:2 offset1:3
	v_mfma_f32_16x16x32_bf16 v[52:55], v[136:139], v[184:187], v[52:55]
	v_mfma_f32_16x16x32_bf16 v[40:43], v[140:143], v[188:191], v[40:43]
	v_mfma_f32_16x16x32_bf16 v[36:39], v[140:143], v[192:195], v[36:39]
	v_mfma_f32_16x16x32_bf16 v[40:43], v[144:147], v[180:183], v[40:43]
	v_mfma_f32_16x16x32_bf16 v[36:39], v[144:147], v[184:187], v[36:39]
	s_waitcnt lgkmcnt(0)
	v_mfma_f32_16x16x32_bf16 v[64:67], v[100:103], v[164:167], v[64:67]
	v_add_u32_e32 v95, -1, v95
	v_add_u32_e32 v72, 0xffffffd0, v95
	v_mfma_f32_16x16x32_bf16 v[60:63], v[100:103], v[168:171], v[60:63]
	v_cmp_gt_u32_e64 s[0:1], 64, v72
	v_add_u32_e32 v73, 0xffffffe0, v95
	v_mfma_f32_16x16x32_bf16 v[64:67], v[104:107], v[188:191], v[64:67]
	v_cmp_gt_u32_e64 s[4:5], 64, v73
	v_add_u32_e32 v97, 0xffffff80, v97
	v_mfma_f32_16x16x32_bf16 v[60:63], v[104:107], v[192:195], v[60:63]
	ds_read2_b32 v[180:181], v97 offset0:24 offset1:25
	ds_read2_b32 v[182:183], v97 offset0:26 offset1:27
	v_mfma_f32_16x16x32_bf16 v[48:51], v[108:111], v[164:167], v[48:51]
	ds_read2_b32 v[184:185], v97 offset0:16 offset1:17
	ds_read2_b32 v[186:187], v97 offset0:18 offset1:19
	v_mfma_f32_16x16x32_bf16 v[44:47], v[108:111], v[168:171], v[44:47]
	v_add_u32_e32 v96, 0xffffff60, v96
	v_cndmask_b32_e64 v76, v68, v96, s[0:1]
	v_mfma_f32_16x16x32_bf16 v[48:51], v[112:115], v[188:191], v[48:51]
	ds_read_b128 v[132:135], v76 offset:0
	ds_read_b128 v[136:139], v76 offset:64
	v_mfma_f32_16x16x32_bf16 v[44:47], v[112:115], v[192:195], v[44:47]
	v_cndmask_b32_e64 v77, v69, v96, s[4:5]
	ds_read_b128 v[140:143], v77 offset:2560
	v_mfma_f32_16x16x32_bf16 v[56:59], v[100:103], v[172:175], v[56:59]
	ds_read_b128 v[144:147], v77 offset:2624
	ds_read2_b32 v[188:189], v97 offset0:8 offset1:9
	v_mfma_f32_16x16x32_bf16 v[52:55], v[100:103], v[176:179], v[52:55]
	ds_read2_b32 v[190:191], v97 offset0:10 offset1:11
	ds_read2_b32 v[192:193], v97 offset0:0 offset1:1
	v_mfma_f32_16x16x32_bf16 v[56:59], v[104:107], v[164:167], v[56:59]
	ds_read2_b32 v[194:195], v97 offset0:2 offset1:3
	v_mfma_f32_16x16x32_bf16 v[52:55], v[104:107], v[168:171], v[52:55]
	v_mfma_f32_16x16x32_bf16 v[40:43], v[108:111], v[172:175], v[40:43]
	v_mfma_f32_16x16x32_bf16 v[36:39], v[108:111], v[176:179], v[36:39]
	v_mfma_f32_16x16x32_bf16 v[40:43], v[112:115], v[164:167], v[40:43]
	v_mfma_f32_16x16x32_bf16 v[36:39], v[112:115], v[168:171], v[36:39]
	s_sub_u32 s24, s24, 1
	s_cmp_lg_u32 s24, 0
	s_cbranch_scc1 .Lconv_seg1
	s_waitcnt lgkmcnt(0)
	v_mfma_f32_16x16x32_bf16 v[64:67], v[132:135], v[180:183], v[64:67]
	v_add_u32_e32 v95, -1, v95
	v_add_u32_e32 v72, 0xffffffd0, v95
	v_mfma_f32_16x16x32_bf16 v[60:63], v[132:135], v[184:187], v[60:63]
	v_cmp_gt_u32_e64 s[0:1], 64, v72
	v_add_u32_e32 v73, 0xffffffe0, v95
	v_mfma_f32_16x16x32_bf16 v[64:67], v[136:139], v[172:175], v[64:67]
	v_cmp_gt_u32_e64 s[4:5], 64, v73
	v_add_u32_e32 v97, 0xffffff80, v97
	v_mfma_f32_16x16x32_bf16 v[60:63], v[136:139], v[176:179], v[60:63]
	ds_read2_b32 v[164:165], v97 offset0:24 offset1:25
	ds_read2_b32 v[166:167], v97 offset0:26 offset1:27
	v_mfma_f32_16x16x32_bf16 v[48:51], v[140:143], v[180:183], v[48:51]
	ds_read2_b32 v[168:169], v97 offset0:16 offset1:17
	ds_read2_b32 v[170:171], v97 offset0:18 offset1:19
	v_mfma_f32_16x16x32_bf16 v[44:47], v[140:143], v[184:187], v[44:47]
	v_add_u32_e32 v96, 0xffffff60, v96
	v_cndmask_b32_e64 v76, v68, v96, s[0:1]
	v_mfma_f32_16x16x32_bf16 v[48:51], v[144:147], v[172:175], v[48:51]
	ds_read_b128 v[100:103], v76 offset:0
	ds_read_b128 v[104:107], v76 offset:64
	v_mfma_f32_16x16x32_bf16 v[44:47], v[144:147], v[176:179], v[44:47]
	v_cndmask_b32_e64 v77, v69, v96, s[4:5]
	ds_read_b128 v[108:111], v77 offset:2560
	v_mfma_f32_16x16x32_bf16 v[56:59], v[132:135], v[188:191], v[56:59]
	ds_read_b128 v[112:115], v77 offset:2624
	ds_read2_b32 v[172:173], v97 offset0:8 offset1:9
	v_mfma_f32_16x16x32_bf16 v[52:55], v[132:135], v[192:195], v[52:55]
	ds_read2_b32 v[174:175], v97 offset0:10 offset1:11
	ds_read2_b32 v[176:177], v97 offset0:0 offset1:1
	v_mfma_f32_16x16x32_bf16 v[56:59], v[136:139], v[180:183], v[56:59]
	ds_read2_b32 v[178:179], v97 offset0:2 offset1:3
	v_mfma_f32_16x16x32_bf16 v[52:55], v[136:139], v[184:187], v[52:55]
	v_mfma_f32_16x16x32_bf16 v[40:43], v[140:143], v[188:191], v[40:43]
	v_mfma_f32_16x16x32_bf16 v[36:39], v[140:143], v[192:195], v[36:39]
	v_mfma_f32_16x16x32_bf16 v[40:43], v[144:147], v[180:183], v[40:43]
	v_mfma_f32_16x16x32_bf16 v[36:39], v[144:147], v[184:187], v[36:39]
	s_waitcnt lgkmcnt(0)
; #define MFMA16(a, b, c) __builtin_amdgcn_mfma_f32_16x16x32_bf16(__builtin_bit_cast(bf16x8, (a)), __builtin_bit_cast(bf16x8, (b)), (c), 0, 0, 0)
; DI void hyena_conv_unit(const Params& p, int item, char* smem) {
;     ...
;   auto bfrag = [&](int E) -> u32x4 {
;     int a = 4095 - 16 * E - n + 8 * g;
;     const bf16_t* src = (a & 1) ? (sG1 + (a - 1)) : (sG0 + a);
;     const unsigned* s32 = (const unsigned*)src;
;     u32x4 o = {s32[0], s32[1], s32[2], s32[3]};
;     return o;
;   };
;   for (int d = -63; d <= 63; ++d) {
; #pragma unroll
;     for (int kk = 0; kk < 2; ++kk) {
;       u32x4 bfr[4];
; #pragma unroll
;       for (int nn = 0; nn < 4; ++nn) bfr[nn] = bfrag(4 * d + nn - 2 * kk);
; #pragma unroll
;       for (int rb = 0; rb < 4; ++rb) {
;         if (d >= 16 * rb - 63 && d <= 16 * rb + 15) {
;           int t1 = 16 * rb + n, s1 = t1 - d;
;           u32x4 a = zero4();
;           if (s1 >= 0 && s1 < 64) a = *(const u32x4*)(su + s1 * 72 + 32 * kk + 8 * g);
; #pragma unroll
;           for (int nn = 0; nn < 4; ++nn) acc[rb][nn] = MFMA16(a, bfr[nn], acc[rb][nn]);
;         }
;       }
;     }
;   }
	v_mfma_f32_16x16x32_bf16 v[64:67], v[100:103], v[164:167], v[64:67]
	v_add_u32_e32 v95, -1, v95
	v_add_u32_e32 v72, 0xffffffd0, v95
	v_cmp_gt_u32_e64 s[0:1], 64, v72
	v_mfma_f32_16x16x32_bf16 v[60:63], v[100:103], v[168:171], v[60:63]
	v_add_u32_e32 v73, 0xffffffe0, v95
	v_cmp_gt_u32_e64 s[4:5], 64, v73
	v_add_u32_e32 v74, 0xfffffff0, v95
	v_mfma_f32_16x16x32_bf16 v[64:67], v[104:107], v[188:191], v[64:67]
	v_cmp_gt_u32_e64 s[6:7], 64, v74
	v_add_u32_e32 v97, 0xffffff80, v97
	ds_read2_b32 v[180:181], v97 offset0:24 offset1:25
	v_mfma_f32_16x16x32_bf16 v[60:63], v[104:107], v[192:195], v[60:63]
	ds_read2_b32 v[182:183], v97 offset0:26 offset1:27
	ds_read2_b32 v[184:185], v97 offset0:16 offset1:17
	ds_read2_b32 v[186:187], v97 offset0:18 offset1:19
	v_mfma_f32_16x16x32_bf16 v[48:51], v[108:111], v[164:167], v[48:51]
	v_add_u32_e32 v96, 0xffffff60, v96
	v_cndmask_b32_e64 v76, v68, v96, s[0:1]
	ds_read_b128 v[132:135], v76 offset:0
	v_mfma_f32_16x16x32_bf16 v[44:47], v[108:111], v[168:171], v[44:47]
	ds_read_b128 v[136:139], v76 offset:64
	v_cndmask_b32_e64 v77, v69, v96, s[4:5]
	ds_read_b128 v[140:143], v77 offset:2560
	v_mfma_f32_16x16x32_bf16 v[48:51], v[112:115], v[188:191], v[48:51]
	ds_read_b128 v[144:147], v77 offset:2624
	v_cndmask_b32_e64 v78, v70, v96, s[6:7]
	ds_read_b128 v[148:151], v78 offset:5120
	v_mfma_f32_16x16x32_bf16 v[44:47], v[112:115], v[192:195], v[44:47]
	ds_read_b128 v[152:155], v78 offset:5184
	ds_read2_b32 v[188:189], v97 offset0:8 offset1:9
	ds_read2_b32 v[190:191], v97 offset0:10 offset1:11
	v_mfma_f32_16x16x32_bf16 v[56:59], v[100:103], v[172:175], v[56:59]
	ds_read2_b32 v[192:193], v97 offset0:0 offset1:1
	ds_read2_b32 v[194:195], v97 offset0:2 offset1:3
	v_mfma_f32_16x16x32_bf16 v[52:55], v[100:103], v[176:179], v[52:55]
	v_mfma_f32_16x16x32_bf16 v[56:59], v[104:107], v[164:167], v[56:59]
	v_mfma_f32_16x16x32_bf16 v[52:55], v[104:107], v[168:171], v[52:55]
	v_mfma_f32_16x16x32_bf16 v[40:43], v[108:111], v[172:175], v[40:43]
	v_mfma_f32_16x16x32_bf16 v[36:39], v[108:111], v[176:179], v[36:39]
	v_mfma_f32_16x16x32_bf16 v[40:43], v[112:115], v[164:167], v[40:43]
	v_mfma_f32_16x16x32_bf16 v[36:39], v[112:115], v[168:171], v[36:39]
	s_mov_b32 s24, 7
.Lconv_seg2:
	s_waitcnt lgkmcnt(0)
	v_mfma_f32_16x16x32_bf16 v[64:67], v[132:135], v[180:183], v[64:67]
	v_add_u32_e32 v95, -1, v95
	v_add_u32_e32 v72, 0xffffffd0, v95
	v_mfma_f32_16x16x32_bf16 v[60:63], v[132:135], v[184:187], v[60:63]
	v_cmp_gt_u32_e64 s[0:1], 64, v72
	v_add_u32_e32 v73, 0xffffffe0, v95
	v_mfma_f32_16x16x32_bf16 v[64:67], v[136:139], v[172:175], v[64:67]
	v_cmp_gt_u32_e64 s[4:5], 64, v73
	v_add_u32_e32 v74, 0xfffffff0, v95
	v_mfma_f32_16x16x32_bf16 v[60:63], v[136:139], v[176:179], v[60:63]
	v_cmp_gt_u32_e64 s[6:7], 64, v74
	v_add_u32_e32 v97, 0xffffff80, v97
	v_mfma_f32_16x16x32_bf16 v[48:51], v[140:143], v[180:183], v[48:51]
	ds_read2_b32 v[164:165], v97 offset0:24 offset1:25
	ds_read2_b32 v[166:167], v97 offset0:26 offset1:27
	v_mfma_f32_16x16x32_bf16 v[44:47], v[140:143], v[184:187], v[44:47]
	ds_read2_b32 v[168:169], v97 offset0:16 offset1:17
	ds_read2_b32 v[170:171], v97 offset0:18 offset1:19
	v_mfma_f32_16x16x32_bf16 v[48:51], v[144:147], v[172:175], v[48:51]
	v_add_u32_e32 v96, 0xffffff60, v96
	v_cndmask_b32_e64 v76, v68, v96, s[0:1]
	v_mfma_f32_16x16x32_bf16 v[44:47], v[144:147], v[176:179], v[44:47]
	ds_read_b128 v[100:103], v76 offset:0
	ds_read_b128 v[104:107], v76 offset:64
	v_mfma_f32_16x16x32_bf16 v[32:35], v[148:151], v[180:183], v[32:35]
	v_cndmask_b32_e64 v77, v69, v96, s[4:5]
	ds_read_b128 v[108:111], v77 offset:2560
	v_mfma_f32_16x16x32_bf16 v[28:31], v[148:151], v[184:187], v[28:31]
	ds_read_b128 v[112:115], v77 offset:2624
	v_cndmask_b32_e64 v78, v70, v96, s[6:7]
	v_mfma_f32_16x16x32_bf16 v[32:35], v[152:155], v[172:175], v[32:35]
	ds_read_b128 v[116:119], v78 offset:5120
	ds_read_b128 v[120:123], v78 offset:5184
	v_mfma_f32_16x16x32_bf16 v[28:31], v[152:155], v[176:179], v[28:31]
	ds_read2_b32 v[172:173], v97 offset0:8 offset1:9
	ds_read2_b32 v[174:175], v97 offset0:10 offset1:11
	v_mfma_f32_16x16x32_bf16 v[56:59], v[132:135], v[188:191], v[56:59]
	ds_read2_b32 v[176:177], v97 offset0:0 offset1:1
	ds_read2_b32 v[178:179], v97 offset0:2 offset1:3
	v_mfma_f32_16x16x32_bf16 v[52:55], v[132:135], v[192:195], v[52:55]
	v_mfma_f32_16x16x32_bf16 v[56:59], v[136:139], v[180:183], v[56:59]
	v_mfma_f32_16x16x32_bf16 v[52:55], v[136:139], v[184:187], v[52:55]
	v_mfma_f32_16x16x32_bf16 v[40:43], v[140:143], v[188:191], v[40:43]
	v_mfma_f32_16x16x32_bf16 v[36:39], v[140:143], v[192:195], v[36:39]
	v_mfma_f32_16x16x32_bf16 v[40:43], v[144:147], v[180:183], v[40:43]
	v_mfma_f32_16x16x32_bf16 v[36:39], v[144:147], v[184:187], v[36:39]
	v_mfma_f32_16x16x32_bf16 v[24:27], v[148:151], v[188:191], v[24:27]
	v_mfma_f32_16x16x32_bf16 v[20:23], v[148:151], v[192:195], v[20:23]
	v_mfma_f32_16x16x32_bf16 v[24:27], v[152:155], v[180:183], v[24:27]
	v_mfma_f32_16x16x32_bf16 v[20:23], v[152:155], v[184:187], v[20:23]
	s_waitcnt lgkmcnt(0)
; #define MFMA16(a, b, c) __builtin_amdgcn_mfma_f32_16x16x32_bf16(__builtin_bit_cast(bf16x8, (a)), __builtin_bit_cast(bf16x8, (b)), (c), 0, 0, 0)
; DI void hyena_conv_unit(const Params& p, int item, char* smem) {
;     ...
;   auto bfrag = [&](int E) -> u32x4 {
;     int a = 4095 - 16 * E - n + 8 * g;
;     const bf16_t* src = (a & 1) ? (sG1 + (a - 1)) : (sG0 + a);
;     const unsigned* s32 = (const unsigned*)src;
;     u32x4 o = {s32[0], s32[1], s32[2], s32[3]};
;     return o;
;   };
;   for (int d = -63; d <= 63; ++d) {
; #pragma unroll
;     for (int kk = 0; kk < 2; ++kk) {
;       u32x4 bfr[4];
; #pragma unroll
;       for (int nn = 0; nn < 4; ++nn) bfr[nn] = bfrag(4 * d + nn - 2 * kk);
; #pragma unroll
;       for (int rb = 0; rb < 4; ++rb) {
;         if (d >= 16 * rb - 63 && d <= 16 * rb + 15) {
;           int t1 = 16 * rb + n, s1 = t1 - d;
;           u32x4 a = zero4();
;           if (s1 >= 0 && s1 < 64) a = *(const u32x4*)(su + s1 * 72 + 32 * kk + 8 * g);
; #pragma unroll
;           for (int nn = 0; nn < 4; ++nn) acc[rb][nn] = MFMA16(a, bfr[nn], acc[rb][nn]);
;         }
;       }
;     }
;   }
	v_mfma_f32_16x16x32_bf16 v[64:67], v[100:103], v[164:167], v[64:67]
	v_add_u32_e32 v95, -1, v95
	v_add_u32_e32 v72, 0xffffffd0, v95
	v_mfma_f32_16x16x32_bf16 v[60:63], v[100:103], v[168:171], v[60:63]
	v_cmp_gt_u32_e64 s[0:1], 64, v72
	v_add_u32_e32 v73, 0xffffffe0, v95
	v_mfma_f32_16x16x32_bf16 v[64:67], v[104:107], v[188:191], v[64:67]
	v_cmp_gt_u32_e64 s[4:5], 64, v73
	v_add_u32_e32 v74, 0xfffffff0, v95
	v_mfma_f32_16x16x32_bf16 v[60:63], v[104:107], v[192:195], v[60:63]
	v_cmp_gt_u32_e64 s[6:7], 64, v74
	v_add_u32_e32 v97, 0xffffff80, v97
	v_mfma_f32_16x16x32_bf16 v[48:51], v[108:111], v[164:167], v[48:51]
	ds_read2_b32 v[180:181], v97 offset0:24 offset1:25
	ds_read2_b32 v[182:183], v97 offset0:26 offset1:27
	v_mfma_f32_16x16x32_bf16 v[44:47], v[108:111], v[168:171], v[44:47]
	ds_read2_b32 v[184:185], v97 offset0:16 offset1:17
	ds_read2_b32 v[186:187], v97 offset0:18 offset1:19
	v_mfma_f32_16x16x32_bf16 v[48:51], v[112:115], v[188:191], v[48:51]
	v_add_u32_e32 v96, 0xffffff60, v96
	v_cndmask_b32_e64 v76, v68, v96, s[0:1]
	v_mfma_f32_16x16x32_bf16 v[44:47], v[112:115], v[192:195], v[44:47]
	ds_read_b128 v[132:135], v76 offset:0
	ds_read_b128 v[136:139], v76 offset:64
	v_mfma_f32_16x16x32_bf16 v[32:35], v[116:119], v[164:167], v[32:35]
	v_cndmask_b32_e64 v77, v69, v96, s[4:5]
	ds_read_b128 v[140:143], v77 offset:2560
	v_mfma_f32_16x16x32_bf16 v[28:31], v[116:119], v[168:171], v[28:31]
	ds_read_b128 v[144:147], v77 offset:2624
	v_cndmask_b32_e64 v78, v70, v96, s[6:7]
	v_mfma_f32_16x16x32_bf16 v[32:35], v[120:123], v[188:191], v[32:35]
	ds_read_b128 v[148:151], v78 offset:5120
	ds_read_b128 v[152:155], v78 offset:5184
	v_mfma_f32_16x16x32_bf16 v[28:31], v[120:123], v[192:195], v[28:31]
	ds_read2_b32 v[188:189], v97 offset0:8 offset1:9
	ds_read2_b32 v[190:191], v97 offset0:10 offset1:11
	v_mfma_f32_16x16x32_bf16 v[56:59], v[100:103], v[172:175], v[56:59]
	ds_read2_b32 v[192:193], v97 offset0:0 offset1:1
	ds_read2_b32 v[194:195], v97 offset0:2 offset1:3
	v_mfma_f32_16x16x32_bf16 v[52:55], v[100:103], v[176:179], v[52:55]
	v_mfma_f32_16x16x32_bf16 v[56:59], v[104:107], v[164:167], v[56:59]
	v_mfma_f32_16x16x32_bf16 v[52:55], v[104:107], v[168:171], v[52:55]
	v_mfma_f32_16x16x32_bf16 v[40:43], v[108:111], v[172:175], v[40:43]
	v_mfma_f32_16x16x32_bf16 v[36:39], v[108:111], v[176:179], v[36:39]
	v_mfma_f32_16x16x32_bf16 v[40:43], v[112:115], v[164:167], v[40:43]
	v_mfma_f32_16x16x32_bf16 v[36:39], v[112:115], v[168:171], v[36:39]
	v_mfma_f32_16x16x32_bf16 v[24:27], v[116:119], v[172:175], v[24:27]
	v_mfma_f32_16x16x32_bf16 v[20:23], v[116:119], v[176:179], v[20:23]
	v_mfma_f32_16x16x32_bf16 v[24:27], v[120:123], v[164:167], v[24:27]
	v_mfma_f32_16x16x32_bf16 v[20:23], v[120:123], v[168:171], v[20:23]
	s_sub_u32 s24, s24, 1
	s_cmp_lg_u32 s24, 0
	s_cbranch_scc1 .Lconv_seg2
	s_waitcnt lgkmcnt(0)
	v_mfma_f32_16x16x32_bf16 v[64:67], v[132:135], v[180:183], v[64:67]
	v_add_u32_e32 v95, -1, v95
	v_add_u32_e32 v72, 0xffffffd0, v95
	v_mfma_f32_16x16x32_bf16 v[60:63], v[132:135], v[184:187], v[60:63]
	v_cmp_gt_u32_e64 s[0:1], 64, v72
	v_add_u32_e32 v73, 0xffffffe0, v95
	v_mfma_f32_16x16x32_bf16 v[64:67], v[136:139], v[172:175], v[64:67]
	v_cmp_gt_u32_e64 s[4:5], 64, v73
	v_add_u32_e32 v74, 0xfffffff0, v95
	v_mfma_f32_16x16x32_bf16 v[60:63], v[136:139], v[176:179], v[60:63]
	v_cmp_gt_u32_e64 s[6:7], 64, v74
	v_add_u32_e32 v97, 0xffffff80, v97
	v_mfma_f32_16x16x32_bf16 v[48:51], v[140:143], v[180:183], v[48:51]
	ds_read2_b32 v[164:165], v97 offset0:24 offset1:25
	ds_read2_b32 v[166:167], v97 offset0:26 offset1:27
	v_mfma_f32_16x16x32_bf16 v[44:47], v[140:143], v[184:187], v[44:47]
	ds_read2_b32 v[168:169], v97 offset0:16 offset1:17
	ds_read2_b32 v[170:171], v97 offset0:18 offset1:19
	v_mfma_f32_16x16x32_bf16 v[48:51], v[144:147], v[172:175], v[48:51]
	v_add_u32_e32 v96, 0xffffff60, v96
	v_cndmask_b32_e64 v76, v68, v96, s[0:1]
	v_mfma_f32_16x16x32_bf16 v[44:47], v[144:147], v[176:179], v[44:47]
	ds_read_b128 v[100:103], v76 offset:0
	ds_read_b128 v[104:107], v76 offset:64
	v_mfma_f32_16x16x32_bf16 v[32:35], v[148:151], v[180:183], v[32:35]
	v_cndmask_b32_e64 v77, v69, v96, s[4:5]
	ds_read_b128 v[108:111], v77 offset:2560
	v_mfma_f32_16x16x32_bf16 v[28:31], v[148:151], v[184:187], v[28:31]
	ds_read_b128 v[112:115], v77 offset:2624
	v_cndmask_b32_e64 v78, v70, v96, s[6:7]
	v_mfma_f32_16x16x32_bf16 v[32:35], v[152:155], v[172:175], v[32:35]
	ds_read_b128 v[116:119], v78 offset:5120
	ds_read_b128 v[120:123], v78 offset:5184
	v_mfma_f32_16x16x32_bf16 v[28:31], v[152:155], v[176:179], v[28:31]
	ds_read2_b32 v[172:173], v97 offset0:8 offset1:9
	ds_read2_b32 v[174:175], v97 offset0:10 offset1:11
	v_mfma_f32_16x16x32_bf16 v[56:59], v[132:135], v[188:191], v[56:59]
	ds_read2_b32 v[176:177], v97 offset0:0 offset1:1
	ds_read2_b32 v[178:179], v97 offset0:2 offset1:3
	v_mfma_f32_16x16x32_bf16 v[52:55], v[132:135], v[192:195], v[52:55]
	v_mfma_f32_16x16x32_bf16 v[56:59], v[136:139], v[180:183], v[56:59]
	v_mfma_f32_16x16x32_bf16 v[52:55], v[136:139], v[184:187], v[52:55]
	v_mfma_f32_16x16x32_bf16 v[40:43], v[140:143], v[188:191], v[40:43]
	v_mfma_f32_16x16x32_bf16 v[36:39], v[140:143], v[192:195], v[36:39]
	v_mfma_f32_16x16x32_bf16 v[40:43], v[144:147], v[180:183], v[40:43]
	v_mfma_f32_16x16x32_bf16 v[36:39], v[144:147], v[184:187], v[36:39]
	v_mfma_f32_16x16x32_bf16 v[24:27], v[148:151], v[188:191], v[24:27]
	v_mfma_f32_16x16x32_bf16 v[20:23], v[148:151], v[192:195], v[20:23]
	v_mfma_f32_16x16x32_bf16 v[24:27], v[152:155], v[180:183], v[24:27]
	v_mfma_f32_16x16x32_bf16 v[20:23], v[152:155], v[184:187], v[20:23]
	s_waitcnt lgkmcnt(0)
; #define MFMA16(a, b, c) __builtin_amdgcn_mfma_f32_16x16x32_bf16(__builtin_bit_cast(bf16x8, (a)), __builtin_bit_cast(bf16x8, (b)), (c), 0, 0, 0)
; DI void hyena_conv_unit(const Params& p, int item, char* smem) {
;     ...
;   auto bfrag = [&](int E) -> u32x4 {
;     int a = 4095 - 16 * E - n + 8 * g;
;     const bf16_t* src = (a & 1) ? (sG1 + (a - 1)) : (sG0 + a);
;     const unsigned* s32 = (const unsigned*)src;
;     u32x4 o = {s32[0], s32[1], s32[2], s32[3]};
;     return o;
;   };
;   for (int d = -63; d <= 63; ++d) {
; #pragma unroll
;     for (int kk = 0; kk < 2; ++kk) {
;       u32x4 bfr[4];
; #pragma unroll
;       for (int nn = 0; nn < 4; ++nn) bfr[nn] = bfrag(4 * d + nn - 2 * kk);
; #pragma unroll
;       for (int rb = 0; rb < 4; ++rb) {
;         if (d >= 16 * rb - 63 && d <= 16 * rb + 15) {
;           int t1 = 16 * rb + n, s1 = t1 - d;
;           u32x4 a = zero4();
;           if (s1 >= 0 && s1 < 64) a = *(const u32x4*)(su + s1 * 72 + 32 * kk + 8 * g);
; #pragma unroll
;           for (int nn = 0; nn < 4; ++nn) acc[rb][nn] = MFMA16(a, bfr[nn], acc[rb][nn]);
;         }
;       }
;     }
;   }
	v_mfma_f32_16x16x32_bf16 v[64:67], v[100:103], v[164:167], v[64:67]
	v_add_u32_e32 v95, -1, v95
	v_add_u32_e32 v72, 0xffffffd0, v95
	v_mfma_f32_16x16x32_bf16 v[60:63], v[100:103], v[168:171], v[60:63]
	v_cmp_gt_u32_e64 s[0:1], 64, v72
	v_add_u32_e32 v73, 0xffffffe0, v95
	v_mfma_f32_16x16x32_bf16 v[64:67], v[104:107], v[188:191], v[64:67]
	v_cmp_gt_u32_e64 s[4:5], 64, v73
	v_add_u32_e32 v74, 0xfffffff0, v95
	v_mfma_f32_16x16x32_bf16 v[60:63], v[104:107], v[192:195], v[60:63]
	v_cmp_gt_u32_e64 s[6:7], 64, v74
	v_cmp_gt_u32_e64 s[20:21], 64, v95
	v_mfma_f32_16x16x32_bf16 v[48:51], v[108:111], v[164:167], v[48:51]
	v_add_u32_e32 v97, 0xffffff80, v97
	ds_read2_b32 v[180:181], v97 offset0:24 offset1:25
	v_mfma_f32_16x16x32_bf16 v[44:47], v[108:111], v[168:171], v[44:47]
	ds_read2_b32 v[182:183], v97 offset0:26 offset1:27
	ds_read2_b32 v[184:185], v97 offset0:16 offset1:17
	v_mfma_f32_16x16x32_bf16 v[48:51], v[112:115], v[188:191], v[48:51]
	ds_read2_b32 v[186:187], v97 offset0:18 offset1:19
	v_add_u32_e32 v96, 0xffffff60, v96
	v_mfma_f32_16x16x32_bf16 v[44:47], v[112:115], v[192:195], v[44:47]
	v_cndmask_b32_e64 v76, v68, v96, s[0:1]
	ds_read_b128 v[132:135], v76 offset:0
	v_mfma_f32_16x16x32_bf16 v[32:35], v[116:119], v[164:167], v[32:35]
	ds_read_b128 v[136:139], v76 offset:64
	v_cndmask_b32_e64 v77, v69, v96, s[4:5]
	v_mfma_f32_16x16x32_bf16 v[28:31], v[116:119], v[168:171], v[28:31]
	ds_read_b128 v[140:143], v77 offset:2560
	ds_read_b128 v[144:147], v77 offset:2624
	v_mfma_f32_16x16x32_bf16 v[32:35], v[120:123], v[188:191], v[32:35]
	v_cndmask_b32_e64 v78, v70, v96, s[6:7]
	ds_read_b128 v[148:151], v78 offset:5120
	v_mfma_f32_16x16x32_bf16 v[28:31], v[120:123], v[192:195], v[28:31]
	ds_read_b128 v[152:155], v78 offset:5184
	v_cndmask_b32_e64 v79, v71, v96, s[20:21]
	v_mfma_f32_16x16x32_bf16 v[56:59], v[100:103], v[172:175], v[56:59]
	ds_read_b128 v[156:159], v79 offset:7680
	ds_read_b128 v[160:163], v79 offset:7744
	v_mfma_f32_16x16x32_bf16 v[52:55], v[100:103], v[176:179], v[52:55]
	ds_read2_b32 v[188:189], v97 offset0:8 offset1:9
	ds_read2_b32 v[190:191], v97 offset0:10 offset1:11
	v_mfma_f32_16x16x32_bf16 v[56:59], v[104:107], v[164:167], v[56:59]
	ds_read2_b32 v[192:193], v97 offset0:0 offset1:1
	ds_read2_b32 v[194:195], v97 offset0:2 offset1:3
	v_mfma_f32_16x16x32_bf16 v[52:55], v[104:107], v[168:171], v[52:55]
	v_mfma_f32_16x16x32_bf16 v[40:43], v[108:111], v[172:175], v[40:43]
	v_mfma_f32_16x16x32_bf16 v[36:39], v[108:111], v[176:179], v[36:39]
	v_mfma_f32_16x16x32_bf16 v[40:43], v[112:115], v[164:167], v[40:43]
	v_mfma_f32_16x16x32_bf16 v[36:39], v[112:115], v[168:171], v[36:39]
	v_mfma_f32_16x16x32_bf16 v[24:27], v[116:119], v[172:175], v[24:27]
	v_mfma_f32_16x16x32_bf16 v[20:23], v[116:119], v[176:179], v[20:23]
	v_mfma_f32_16x16x32_bf16 v[24:27], v[120:123], v[164:167], v[24:27]
	v_mfma_f32_16x16x32_bf16 v[20:23], v[120:123], v[168:171], v[20:23]
	s_mov_b32 s24, 15
.Lconv_seg3:
	s_waitcnt lgkmcnt(0)
	v_mfma_f32_16x16x32_bf16 v[64:67], v[132:135], v[180:183], v[64:67]
	v_add_u32_e32 v95, -1, v95
	v_add_u32_e32 v72, 0xffffffd0, v95
	v_mfma_f32_16x16x32_bf16 v[60:63], v[132:135], v[184:187], v[60:63]
	v_cmp_gt_u32_e64 s[0:1], 64, v72
	v_add_u32_e32 v73, 0xffffffe0, v95
	v_mfma_f32_16x16x32_bf16 v[64:67], v[136:139], v[172:175], v[64:67]
	v_cmp_gt_u32_e64 s[4:5], 64, v73
	v_add_u32_e32 v74, 0xfffffff0, v95
	v_mfma_f32_16x16x32_bf16 v[60:63], v[136:139], v[176:179], v[60:63]
	v_cmp_gt_u32_e64 s[6:7], 64, v74
	v_cmp_gt_u32_e64 s[20:21], 64, v95
	v_mfma_f32_16x16x32_bf16 v[48:51], v[140:143], v[180:183], v[48:51]
	v_add_u32_e32 v97, 0xffffff80, v97
	ds_read2_b32 v[164:165], v97 offset0:24 offset1:25
	v_mfma_f32_16x16x32_bf16 v[44:47], v[140:143], v[184:187], v[44:47]
	ds_read2_b32 v[166:167], v97 offset0:26 offset1:27
	ds_read2_b32 v[168:169], v97 offset0:16 offset1:17
	v_mfma_f32_16x16x32_bf16 v[48:51], v[144:147], v[172:175], v[48:51]
	ds_read2_b32 v[170:171], v97 offset0:18 offset1:19
	v_add_u32_e32 v96, 0xffffff60, v96
	v_mfma_f32_16x16x32_bf16 v[44:47], v[144:147], v[176:179], v[44:47]
	v_cndmask_b32_e64 v76, v68, v96, s[0:1]
	ds_read_b128 v[100:103], v76 offset:0
	v_mfma_f32_16x16x32_bf16 v[32:35], v[148:151], v[180:183], v[32:35]
	ds_read_b128 v[104:107], v76 offset:64
	v_cndmask_b32_e64 v77, v69, v96, s[4:5]
	v_mfma_f32_16x16x32_bf16 v[28:31], v[148:151], v[184:187], v[28:31]
	ds_read_b128 v[108:111], v77 offset:2560
	ds_read_b128 v[112:115], v77 offset:2624
	v_mfma_f32_16x16x32_bf16 v[32:35], v[152:155], v[172:175], v[32:35]
	v_cndmask_b32_e64 v78, v70, v96, s[6:7]
	ds_read_b128 v[116:119], v78 offset:5120
	v_mfma_f32_16x16x32_bf16 v[28:31], v[152:155], v[176:179], v[28:31]
	ds_read_b128 v[120:123], v78 offset:5184
	v_cndmask_b32_e64 v79, v71, v96, s[20:21]
	v_mfma_f32_16x16x32_bf16 v[16:19], v[156:159], v[180:183], v[16:19]
	ds_read_b128 v[124:127], v79 offset:7680
	ds_read_b128 v[128:131], v79 offset:7744
	v_mfma_f32_16x16x32_bf16 v[12:15], v[156:159], v[184:187], v[12:15]
	v_mfma_f32_16x16x32_bf16 v[16:19], v[160:163], v[172:175], v[16:19]
	v_mfma_f32_16x16x32_bf16 v[12:15], v[160:163], v[176:179], v[12:15]
	ds_read2_b32 v[172:173], v97 offset0:8 offset1:9
	ds_read2_b32 v[174:175], v97 offset0:10 offset1:11
	v_mfma_f32_16x16x32_bf16 v[56:59], v[132:135], v[188:191], v[56:59]
	ds_read2_b32 v[176:177], v97 offset0:0 offset1:1
	ds_read2_b32 v[178:179], v97 offset0:2 offset1:3
	v_mfma_f32_16x16x32_bf16 v[52:55], v[132:135], v[192:195], v[52:55]
	v_mfma_f32_16x16x32_bf16 v[56:59], v[136:139], v[180:183], v[56:59]
	v_mfma_f32_16x16x32_bf16 v[52:55], v[136:139], v[184:187], v[52:55]
	v_mfma_f32_16x16x32_bf16 v[40:43], v[140:143], v[188:191], v[40:43]
	v_mfma_f32_16x16x32_bf16 v[36:39], v[140:143], v[192:195], v[36:39]
	v_mfma_f32_16x16x32_bf16 v[40:43], v[144:147], v[180:183], v[40:43]
	v_mfma_f32_16x16x32_bf16 v[36:39], v[144:147], v[184:187], v[36:39]
	v_mfma_f32_16x16x32_bf16 v[24:27], v[148:151], v[188:191], v[24:27]
	v_mfma_f32_16x16x32_bf16 v[20:23], v[148:151], v[192:195], v[20:23]
	v_mfma_f32_16x16x32_bf16 v[24:27], v[152:155], v[180:183], v[24:27]
	v_mfma_f32_16x16x32_bf16 v[20:23], v[152:155], v[184:187], v[20:23]
	v_mfma_f32_16x16x32_bf16 v[8:11], v[156:159], v[188:191], v[8:11]
	v_mfma_f32_16x16x32_bf16 v[4:7], v[156:159], v[192:195], v[4:7]
	v_mfma_f32_16x16x32_bf16 v[8:11], v[160:163], v[180:183], v[8:11]
	v_mfma_f32_16x16x32_bf16 v[4:7], v[160:163], v[184:187], v[4:7]
	s_waitcnt lgkmcnt(0)
; #define MFMA16(a, b, c) __builtin_amdgcn_mfma_f32_16x16x32_bf16(__builtin_bit_cast(bf16x8, (a)), __builtin_bit_cast(bf16x8, (b)), (c), 0, 0, 0)
; DI void hyena_conv_unit(const Params& p, int item, char* smem) {
;     ...
;   auto bfrag = [&](int E) -> u32x4 {
;     int a = 4095 - 16 * E - n + 8 * g;
;     const bf16_t* src = (a & 1) ? (sG1 + (a - 1)) : (sG0 + a);
;     const unsigned* s32 = (const unsigned*)src;
;     u32x4 o = {s32[0], s32[1], s32[2], s32[3]};
;     return o;
;   };
;   for (int d = -63; d <= 63; ++d) {
; #pragma unroll
;     for (int kk = 0; kk < 2; ++kk) {
;       u32x4 bfr[4];
; #pragma unroll
;       for (int nn = 0; nn < 4; ++nn) bfr[nn] = bfrag(4 * d + nn - 2 * kk);
; #pragma unroll
;       for (int rb = 0; rb < 4; ++rb) {
;         if (d >= 16 * rb - 63 && d <= 16 * rb + 15) {
;           int t1 = 16 * rb + n, s1 = t1 - d;
;           u32x4 a = zero4();
;           if (s1 >= 0 && s1 < 64) a = *(const u32x4*)(su + s1 * 72 + 32 * kk + 8 * g);
; #pragma unroll
;           for (int nn = 0; nn < 4; ++nn) acc[rb][nn] = MFMA16(a, bfr[nn], acc[rb][nn]);
;         }
;       }
;     }
;   }
	v_mfma_f32_16x16x32_bf16 v[64:67], v[100:103], v[164:167], v[64:67]
	v_add_u32_e32 v95, -1, v95
	v_add_u32_e32 v72, 0xffffffd0, v95
	v_mfma_f32_16x16x32_bf16 v[60:63], v[100:103], v[168:171], v[60:63]
	v_cmp_gt_u32_e64 s[0:1], 64, v72
	v_add_u32_e32 v73, 0xffffffe0, v95
	v_mfma_f32_16x16x32_bf16 v[64:67], v[104:107], v[188:191], v[64:67]
	v_cmp_gt_u32_e64 s[4:5], 64, v73
	v_add_u32_e32 v74, 0xfffffff0, v95
	v_mfma_f32_16x16x32_bf16 v[60:63], v[104:107], v[192:195], v[60:63]
	v_cmp_gt_u32_e64 s[6:7], 64, v74
	v_cmp_gt_u32_e64 s[20:21], 64, v95
	v_mfma_f32_16x16x32_bf16 v[48:51], v[108:111], v[164:167], v[48:51]
	v_add_u32_e32 v97, 0xffffff80, v97
	ds_read2_b32 v[180:181], v97 offset0:24 offset1:25
	v_mfma_f32_16x16x32_bf16 v[44:47], v[108:111], v[168:171], v[44:47]
	ds_read2_b32 v[182:183], v97 offset0:26 offset1:27
	ds_read2_b32 v[184:185], v97 offset0:16 offset1:17
	v_mfma_f32_16x16x32_bf16 v[48:51], v[112:115], v[188:191], v[48:51]
	ds_read2_b32 v[186:187], v97 offset0:18 offset1:19
	v_add_u32_e32 v96, 0xffffff60, v96
	v_mfma_f32_16x16x32_bf16 v[44:47], v[112:115], v[192:195], v[44:47]
	v_cndmask_b32_e64 v76, v68, v96, s[0:1]
	ds_read_b128 v[132:135], v76 offset:0
	v_mfma_f32_16x16x32_bf16 v[32:35], v[116:119], v[164:167], v[32:35]
	ds_read_b128 v[136:139], v76 offset:64
	v_cndmask_b32_e64 v77, v69, v96, s[4:5]
	v_mfma_f32_16x16x32_bf16 v[28:31], v[116:119], v[168:171], v[28:31]
	ds_read_b128 v[140:143], v77 offset:2560
	ds_read_b128 v[144:147], v77 offset:2624
	v_mfma_f32_16x16x32_bf16 v[32:35], v[120:123], v[188:191], v[32:35]
	v_cndmask_b32_e64 v78, v70, v96, s[6:7]
	ds_read_b128 v[148:151], v78 offset:5120
	v_mfma_f32_16x16x32_bf16 v[28:31], v[120:123], v[192:195], v[28:31]
	ds_read_b128 v[152:155], v78 offset:5184
	v_cndmask_b32_e64 v79, v71, v96, s[20:21]
	v_mfma_f32_16x16x32_bf16 v[16:19], v[124:127], v[164:167], v[16:19]
	ds_read_b128 v[156:159], v79 offset:7680
	ds_read_b128 v[160:163], v79 offset:7744
	v_mfma_f32_16x16x32_bf16 v[12:15], v[124:127], v[168:171], v[12:15]
	v_mfma_f32_16x16x32_bf16 v[16:19], v[128:131], v[188:191], v[16:19]
	v_mfma_f32_16x16x32_bf16 v[12:15], v[128:131], v[192:195], v[12:15]
	ds_read2_b32 v[188:189], v97 offset0:8 offset1:9
	ds_read2_b32 v[190:191], v97 offset0:10 offset1:11
	v_mfma_f32_16x16x32_bf16 v[56:59], v[100:103], v[172:175], v[56:59]
	ds_read2_b32 v[192:193], v97 offset0:0 offset1:1
	ds_read2_b32 v[194:195], v97 offset0:2 offset1:3
	v_mfma_f32_16x16x32_bf16 v[52:55], v[100:103], v[176:179], v[52:55]
	v_mfma_f32_16x16x32_bf16 v[56:59], v[104:107], v[164:167], v[56:59]
	v_mfma_f32_16x16x32_bf16 v[52:55], v[104:107], v[168:171], v[52:55]
	v_mfma_f32_16x16x32_bf16 v[40:43], v[108:111], v[172:175], v[40:43]
	v_mfma_f32_16x16x32_bf16 v[36:39], v[108:111], v[176:179], v[36:39]
	v_mfma_f32_16x16x32_bf16 v[40:43], v[112:115], v[164:167], v[40:43]
	v_mfma_f32_16x16x32_bf16 v[36:39], v[112:115], v[168:171], v[36:39]
	v_mfma_f32_16x16x32_bf16 v[24:27], v[116:119], v[172:175], v[24:27]
	v_mfma_f32_16x16x32_bf16 v[20:23], v[116:119], v[176:179], v[20:23]
	v_mfma_f32_16x16x32_bf16 v[24:27], v[120:123], v[164:167], v[24:27]
	v_mfma_f32_16x16x32_bf16 v[20:23], v[120:123], v[168:171], v[20:23]
	v_mfma_f32_16x16x32_bf16 v[8:11], v[124:127], v[172:175], v[8:11]
	v_mfma_f32_16x16x32_bf16 v[4:7], v[124:127], v[176:179], v[4:7]
	v_mfma_f32_16x16x32_bf16 v[8:11], v[128:131], v[164:167], v[8:11]
	v_mfma_f32_16x16x32_bf16 v[4:7], v[128:131], v[168:171], v[4:7]
	s_sub_u32 s24, s24, 1
	s_cmp_lg_u32 s24, 0
	s_cbranch_scc1 .Lconv_seg3
	s_waitcnt lgkmcnt(0)
	v_mfma_f32_16x16x32_bf16 v[64:67], v[132:135], v[180:183], v[64:67]
	v_add_u32_e32 v95, -1, v95
	v_add_u32_e32 v72, 0xffffffd0, v95
	v_mfma_f32_16x16x32_bf16 v[60:63], v[132:135], v[184:187], v[60:63]
	v_cmp_gt_u32_e64 s[0:1], 64, v72
	v_add_u32_e32 v73, 0xffffffe0, v95
	v_mfma_f32_16x16x32_bf16 v[64:67], v[136:139], v[172:175], v[64:67]
	v_cmp_gt_u32_e64 s[4:5], 64, v73
	v_add_u32_e32 v74, 0xfffffff0, v95
	v_mfma_f32_16x16x32_bf16 v[60:63], v[136:139], v[176:179], v[60:63]
	v_cmp_gt_u32_e64 s[6:7], 64, v74
	v_cmp_gt_u32_e64 s[20:21], 64, v95
	v_mfma_f32_16x16x32_bf16 v[48:51], v[140:143], v[180:183], v[48:51]
	v_add_u32_e32 v97, 0xffffff80, v97
	ds_read2_b32 v[164:165], v97 offset0:24 offset1:25
	v_mfma_f32_16x16x32_bf16 v[44:47], v[140:143], v[184:187], v[44:47]
	ds_read2_b32 v[166:167], v97 offset0:26 offset1:27
	ds_read2_b32 v[168:169], v97 offset0:16 offset1:17
	v_mfma_f32_16x16x32_bf16 v[48:51], v[144:147], v[172:175], v[48:51]
	ds_read2_b32 v[170:171], v97 offset0:18 offset1:19
	v_add_u32_e32 v96, 0xffffff60, v96
	v_mfma_f32_16x16x32_bf16 v[44:47], v[144:147], v[176:179], v[44:47]
	v_cndmask_b32_e64 v76, v68, v96, s[0:1]
	ds_read_b128 v[100:103], v76 offset:0
	v_mfma_f32_16x16x32_bf16 v[32:35], v[148:151], v[180:183], v[32:35]
	ds_read_b128 v[104:107], v76 offset:64
	v_cndmask_b32_e64 v77, v69, v96, s[4:5]
	v_mfma_f32_16x16x32_bf16 v[28:31], v[148:151], v[184:187], v[28:31]
	ds_read_b128 v[108:111], v77 offset:2560
	ds_read_b128 v[112:115], v77 offset:2624
	v_mfma_f32_16x16x32_bf16 v[32:35], v[152:155], v[172:175], v[32:35]
	v_cndmask_b32_e64 v78, v70, v96, s[6:7]
	ds_read_b128 v[116:119], v78 offset:5120
	v_mfma_f32_16x16x32_bf16 v[28:31], v[152:155], v[176:179], v[28:31]
	ds_read_b128 v[120:123], v78 offset:5184
	v_cndmask_b32_e64 v79, v71, v96, s[20:21]
	v_mfma_f32_16x16x32_bf16 v[16:19], v[156:159], v[180:183], v[16:19]
	ds_read_b128 v[124:127], v79 offset:7680
	ds_read_b128 v[128:131], v79 offset:7744
	v_mfma_f32_16x16x32_bf16 v[12:15], v[156:159], v[184:187], v[12:15]
	v_mfma_f32_16x16x32_bf16 v[16:19], v[160:163], v[172:175], v[16:19]
	v_mfma_f32_16x16x32_bf16 v[12:15], v[160:163], v[176:179], v[12:15]
	ds_read2_b32 v[172:173], v97 offset0:8 offset1:9
	ds_read2_b32 v[174:175], v97 offset0:10 offset1:11
	v_mfma_f32_16x16x32_bf16 v[56:59], v[132:135], v[188:191], v[56:59]
	ds_read2_b32 v[176:177], v97 offset0:0 offset1:1
	ds_read2_b32 v[178:179], v97 offset0:2 offset1:3
	v_mfma_f32_16x16x32_bf16 v[52:55], v[132:135], v[192:195], v[52:55]
	v_mfma_f32_16x16x32_bf16 v[56:59], v[136:139], v[180:183], v[56:59]
	v_mfma_f32_16x16x32_bf16 v[52:55], v[136:139], v[184:187], v[52:55]
	v_mfma_f32_16x16x32_bf16 v[40:43], v[140:143], v[188:191], v[40:43]
	v_mfma_f32_16x16x32_bf16 v[36:39], v[140:143], v[192:195], v[36:39]
	v_mfma_f32_16x16x32_bf16 v[40:43], v[144:147], v[180:183], v[40:43]
	v_mfma_f32_16x16x32_bf16 v[36:39], v[144:147], v[184:187], v[36:39]
	v_mfma_f32_16x16x32_bf16 v[24:27], v[148:151], v[188:191], v[24:27]
	v_mfma_f32_16x16x32_bf16 v[20:23], v[148:151], v[192:195], v[20:23]
	v_mfma_f32_16x16x32_bf16 v[24:27], v[152:155], v[180:183], v[24:27]
	v_mfma_f32_16x16x32_bf16 v[20:23], v[152:155], v[184:187], v[20:23]
	v_mfma_f32_16x16x32_bf16 v[8:11], v[156:159], v[188:191], v[8:11]
	v_mfma_f32_16x16x32_bf16 v[4:7], v[156:159], v[192:195], v[4:7]
	v_mfma_f32_16x16x32_bf16 v[8:11], v[160:163], v[180:183], v[8:11]
	v_mfma_f32_16x16x32_bf16 v[4:7], v[160:163], v[184:187], v[4:7]
	s_waitcnt lgkmcnt(0)
; #define MFMA16(a, b, c) __builtin_amdgcn_mfma_f32_16x16x32_bf16(__builtin_bit_cast(bf16x8, (a)), __builtin_bit_cast(bf16x8, (b)), (c), 0, 0, 0)
; DI void hyena_conv_unit(const Params& p, int item, char* smem) {
;     ...
;   for (int d = -63; d <= 63; ++d) {
; #pragma unroll
;     for (int kk = 0; kk < 2; ++kk) {
;       u32x4 bfr[4];
; #pragma unroll
;       for (int nn = 0; nn < 4; ++nn) bfr[nn] = bfrag(4 * d + nn - 2 * kk);
; #pragma unroll
;       for (int rb = 0; rb < 4; ++rb) {
;         if (d >= 16 * rb - 63 && d <= 16 * rb + 15) {
;           int t1 = 16 * rb + n, s1 = t1 - d;
;           u32x4 a = zero4();
;           if (s1 >= 0 && s1 < 64) a = *(const u32x4*)(su + s1 * 72 + 32 * kk + 8 * g);
; #pragma unroll
;           for (int nn = 0; nn < 4; ++nn) acc[rb][nn] = MFMA16(a, bfr[nn], acc[rb][nn]);
;         }
;       }
;     }
;   }
	v_mfma_f32_16x16x32_bf16 v[64:67], v[100:103], v[164:167], v[64:67]
	v_add_u32_e32 v95, -1, v95
	v_add_u32_e32 v73, 0xffffffe0, v95
	v_mfma_f32_16x16x32_bf16 v[60:63], v[100:103], v[168:171], v[60:63]
	v_cmp_gt_u32_e64 s[4:5], 64, v73
	v_add_u32_e32 v74, 0xfffffff0, v95
	v_mfma_f32_16x16x32_bf16 v[64:67], v[104:107], v[188:191], v[64:67]
	v_cmp_gt_u32_e64 s[6:7], 64, v74
	v_cmp_gt_u32_e64 s[20:21], 64, v95
	v_mfma_f32_16x16x32_bf16 v[60:63], v[104:107], v[192:195], v[60:63]
	v_add_u32_e32 v97, 0xffffff80, v97
	ds_read2_b32 v[180:181], v97 offset0:24 offset1:25
	v_mfma_f32_16x16x32_bf16 v[48:51], v[108:111], v[164:167], v[48:51]
	ds_read2_b32 v[182:183], v97 offset0:26 offset1:27
	ds_read2_b32 v[184:185], v97 offset0:16 offset1:17
	v_mfma_f32_16x16x32_bf16 v[44:47], v[108:111], v[168:171], v[44:47]
	ds_read2_b32 v[186:187], v97 offset0:18 offset1:19
	v_add_u32_e32 v96, 0xffffff60, v96
	v_mfma_f32_16x16x32_bf16 v[48:51], v[112:115], v[188:191], v[48:51]
	v_cndmask_b32_e64 v77, v69, v96, s[4:5]
	ds_read_b128 v[140:143], v77 offset:2560
	v_mfma_f32_16x16x32_bf16 v[44:47], v[112:115], v[192:195], v[44:47]
	ds_read_b128 v[144:147], v77 offset:2624
	v_cndmask_b32_e64 v78, v70, v96, s[6:7]
	v_mfma_f32_16x16x32_bf16 v[32:35], v[116:119], v[164:167], v[32:35]
	ds_read_b128 v[148:151], v78 offset:5120
	ds_read_b128 v[152:155], v78 offset:5184
	v_mfma_f32_16x16x32_bf16 v[28:31], v[116:119], v[168:171], v[28:31]
	v_cndmask_b32_e64 v79, v71, v96, s[20:21]
	ds_read_b128 v[156:159], v79 offset:7680
	v_mfma_f32_16x16x32_bf16 v[32:35], v[120:123], v[188:191], v[32:35]
	ds_read_b128 v[160:163], v79 offset:7744
	v_mfma_f32_16x16x32_bf16 v[28:31], v[120:123], v[192:195], v[28:31]
	v_mfma_f32_16x16x32_bf16 v[16:19], v[124:127], v[164:167], v[16:19]
	v_mfma_f32_16x16x32_bf16 v[12:15], v[124:127], v[168:171], v[12:15]
	v_mfma_f32_16x16x32_bf16 v[16:19], v[128:131], v[188:191], v[16:19]
	v_mfma_f32_16x16x32_bf16 v[12:15], v[128:131], v[192:195], v[12:15]
	ds_read2_b32 v[188:189], v97 offset0:8 offset1:9
	ds_read2_b32 v[190:191], v97 offset0:10 offset1:11
	v_mfma_f32_16x16x32_bf16 v[56:59], v[100:103], v[172:175], v[56:59]
	ds_read2_b32 v[192:193], v97 offset0:0 offset1:1
	ds_read2_b32 v[194:195], v97 offset0:2 offset1:3
	v_mfma_f32_16x16x32_bf16 v[52:55], v[100:103], v[176:179], v[52:55]
	v_mfma_f32_16x16x32_bf16 v[56:59], v[104:107], v[164:167], v[56:59]
	v_mfma_f32_16x16x32_bf16 v[52:55], v[104:107], v[168:171], v[52:55]
	v_mfma_f32_16x16x32_bf16 v[40:43], v[108:111], v[172:175], v[40:43]
	v_mfma_f32_16x16x32_bf16 v[36:39], v[108:111], v[176:179], v[36:39]
	v_mfma_f32_16x16x32_bf16 v[40:43], v[112:115], v[164:167], v[40:43]
	v_mfma_f32_16x16x32_bf16 v[36:39], v[112:115], v[168:171], v[36:39]
	v_mfma_f32_16x16x32_bf16 v[24:27], v[116:119], v[172:175], v[24:27]
	v_mfma_f32_16x16x32_bf16 v[20:23], v[116:119], v[176:179], v[20:23]
	v_mfma_f32_16x16x32_bf16 v[24:27], v[120:123], v[164:167], v[24:27]
	v_mfma_f32_16x16x32_bf16 v[20:23], v[120:123], v[168:171], v[20:23]
	v_mfma_f32_16x16x32_bf16 v[8:11], v[124:127], v[172:175], v[8:11]
	v_mfma_f32_16x16x32_bf16 v[4:7], v[124:127], v[176:179], v[4:7]
	v_mfma_f32_16x16x32_bf16 v[8:11], v[128:131], v[164:167], v[8:11]
	v_mfma_f32_16x16x32_bf16 v[4:7], v[128:131], v[168:171], v[4:7]
	s_mov_b32 s24, 7
.Lconv_seg4:
	s_waitcnt lgkmcnt(0)
	v_mfma_f32_16x16x32_bf16 v[48:51], v[140:143], v[180:183], v[48:51]
	v_add_u32_e32 v95, -1, v95
	v_add_u32_e32 v73, 0xffffffe0, v95
	v_mfma_f32_16x16x32_bf16 v[44:47], v[140:143], v[184:187], v[44:47]
	v_cmp_gt_u32_e64 s[4:5], 64, v73
	v_add_u32_e32 v74, 0xfffffff0, v95
	v_mfma_f32_16x16x32_bf16 v[48:51], v[144:147], v[172:175], v[48:51]
	v_cmp_gt_u32_e64 s[6:7], 64, v74
	v_cmp_gt_u32_e64 s[20:21], 64, v95
	v_mfma_f32_16x16x32_bf16 v[44:47], v[144:147], v[176:179], v[44:47]
	v_add_u32_e32 v97, 0xffffff80, v97
	ds_read2_b32 v[164:165], v97 offset0:24 offset1:25
	v_mfma_f32_16x16x32_bf16 v[32:35], v[148:151], v[180:183], v[32:35]
	ds_read2_b32 v[166:167], v97 offset0:26 offset1:27
	ds_read2_b32 v[168:169], v97 offset0:16 offset1:17
	v_mfma_f32_16x16x32_bf16 v[28:31], v[148:151], v[184:187], v[28:31]
	ds_read2_b32 v[170:171], v97 offset0:18 offset1:19
	v_add_u32_e32 v96, 0xffffff60, v96
	v_mfma_f32_16x16x32_bf16 v[32:35], v[152:155], v[172:175], v[32:35]
	v_cndmask_b32_e64 v77, v69, v96, s[4:5]
	ds_read_b128 v[108:111], v77 offset:2560
	v_mfma_f32_16x16x32_bf16 v[28:31], v[152:155], v[176:179], v[28:31]
	ds_read_b128 v[112:115], v77 offset:2624
	v_cndmask_b32_e64 v78, v70, v96, s[6:7]
	v_mfma_f32_16x16x32_bf16 v[16:19], v[156:159], v[180:183], v[16:19]
	ds_read_b128 v[116:119], v78 offset:5120
	ds_read_b128 v[120:123], v78 offset:5184
	v_mfma_f32_16x16x32_bf16 v[12:15], v[156:159], v[184:187], v[12:15]
	v_cndmask_b32_e64 v79, v71, v96, s[20:21]
	ds_read_b128 v[124:127], v79 offset:7680
	v_mfma_f32_16x16x32_bf16 v[16:19], v[160:163], v[172:175], v[16:19]
	ds_read_b128 v[128:131], v79 offset:7744
	v_mfma_f32_16x16x32_bf16 v[12:15], v[160:163], v[176:179], v[12:15]
	ds_read2_b32 v[172:173], v97 offset0:8 offset1:9
	ds_read2_b32 v[174:175], v97 offset0:10 offset1:11
	v_mfma_f32_16x16x32_bf16 v[40:43], v[140:143], v[188:191], v[40:43]
	ds_read2_b32 v[176:177], v97 offset0:0 offset1:1
	ds_read2_b32 v[178:179], v97 offset0:2 offset1:3
	v_mfma_f32_16x16x32_bf16 v[36:39], v[140:143], v[192:195], v[36:39]
	v_mfma_f32_16x16x32_bf16 v[40:43], v[144:147], v[180:183], v[40:43]
	v_mfma_f32_16x16x32_bf16 v[36:39], v[144:147], v[184:187], v[36:39]
	v_mfma_f32_16x16x32_bf16 v[24:27], v[148:151], v[188:191], v[24:27]
	v_mfma_f32_16x16x32_bf16 v[20:23], v[148:151], v[192:195], v[20:23]
	v_mfma_f32_16x16x32_bf16 v[24:27], v[152:155], v[180:183], v[24:27]
	v_mfma_f32_16x16x32_bf16 v[20:23], v[152:155], v[184:187], v[20:23]
	v_mfma_f32_16x16x32_bf16 v[8:11], v[156:159], v[188:191], v[8:11]
	v_mfma_f32_16x16x32_bf16 v[4:7], v[156:159], v[192:195], v[4:7]
	v_mfma_f32_16x16x32_bf16 v[8:11], v[160:163], v[180:183], v[8:11]
	v_mfma_f32_16x16x32_bf16 v[4:7], v[160:163], v[184:187], v[4:7]
	s_waitcnt lgkmcnt(0)
; #define MFMA16(a, b, c) __builtin_amdgcn_mfma_f32_16x16x32_bf16(__builtin_bit_cast(bf16x8, (a)), __builtin_bit_cast(bf16x8, (b)), (c), 0, 0, 0)
; DI void hyena_conv_unit(const Params& p, int item, char* smem) {
;     ...
;   for (int d = -63; d <= 63; ++d) {
; #pragma unroll
;     for (int kk = 0; kk < 2; ++kk) {
;       u32x4 bfr[4];
; #pragma unroll
;       for (int nn = 0; nn < 4; ++nn) bfr[nn] = bfrag(4 * d + nn - 2 * kk);
; #pragma unroll
;       for (int rb = 0; rb < 4; ++rb) {
;         if (d >= 16 * rb - 63 && d <= 16 * rb + 15) {
;           int t1 = 16 * rb + n, s1 = t1 - d;
;           u32x4 a = zero4();
;           if (s1 >= 0 && s1 < 64) a = *(const u32x4*)(su + s1 * 72 + 32 * kk + 8 * g);
; #pragma unroll
;           for (int nn = 0; nn < 4; ++nn) acc[rb][nn] = MFMA16(a, bfr[nn], acc[rb][nn]);
;         }
;       }
;     }
;   }
	v_mfma_f32_16x16x32_bf16 v[48:51], v[108:111], v[164:167], v[48:51]
	v_add_u32_e32 v95, -1, v95
	v_add_u32_e32 v73, 0xffffffe0, v95
	v_mfma_f32_16x16x32_bf16 v[44:47], v[108:111], v[168:171], v[44:47]
	v_cmp_gt_u32_e64 s[4:5], 64, v73
	v_add_u32_e32 v74, 0xfffffff0, v95
	v_mfma_f32_16x16x32_bf16 v[48:51], v[112:115], v[188:191], v[48:51]
	v_cmp_gt_u32_e64 s[6:7], 64, v74
	v_cmp_gt_u32_e64 s[20:21], 64, v95
	v_mfma_f32_16x16x32_bf16 v[44:47], v[112:115], v[192:195], v[44:47]
	v_add_u32_e32 v97, 0xffffff80, v97
	ds_read2_b32 v[180:181], v97 offset0:24 offset1:25
	v_mfma_f32_16x16x32_bf16 v[32:35], v[116:119], v[164:167], v[32:35]
	ds_read2_b32 v[182:183], v97 offset0:26 offset1:27
	ds_read2_b32 v[184:185], v97 offset0:16 offset1:17
	v_mfma_f32_16x16x32_bf16 v[28:31], v[116:119], v[168:171], v[28:31]
	ds_read2_b32 v[186:187], v97 offset0:18 offset1:19
	v_add_u32_e32 v96, 0xffffff60, v96
	v_mfma_f32_16x16x32_bf16 v[32:35], v[120:123], v[188:191], v[32:35]
	v_cndmask_b32_e64 v77, v69, v96, s[4:5]
	ds_read_b128 v[140:143], v77 offset:2560
	v_mfma_f32_16x16x32_bf16 v[28:31], v[120:123], v[192:195], v[28:31]
	ds_read_b128 v[144:147], v77 offset:2624
	v_cndmask_b32_e64 v78, v70, v96, s[6:7]
	v_mfma_f32_16x16x32_bf16 v[16:19], v[124:127], v[164:167], v[16:19]
	ds_read_b128 v[148:151], v78 offset:5120
	ds_read_b128 v[152:155], v78 offset:5184
	v_mfma_f32_16x16x32_bf16 v[12:15], v[124:127], v[168:171], v[12:15]
	v_cndmask_b32_e64 v79, v71, v96, s[20:21]
	ds_read_b128 v[156:159], v79 offset:7680
	v_mfma_f32_16x16x32_bf16 v[16:19], v[128:131], v[188:191], v[16:19]
	ds_read_b128 v[160:163], v79 offset:7744
	v_mfma_f32_16x16x32_bf16 v[12:15], v[128:131], v[192:195], v[12:15]
	ds_read2_b32 v[188:189], v97 offset0:8 offset1:9
	ds_read2_b32 v[190:191], v97 offset0:10 offset1:11
	v_mfma_f32_16x16x32_bf16 v[40:43], v[108:111], v[172:175], v[40:43]
	ds_read2_b32 v[192:193], v97 offset0:0 offset1:1
	ds_read2_b32 v[194:195], v97 offset0:2 offset1:3
	v_mfma_f32_16x16x32_bf16 v[36:39], v[108:111], v[176:179], v[36:39]
	v_mfma_f32_16x16x32_bf16 v[40:43], v[112:115], v[164:167], v[40:43]
	v_mfma_f32_16x16x32_bf16 v[36:39], v[112:115], v[168:171], v[36:39]
	v_mfma_f32_16x16x32_bf16 v[24:27], v[116:119], v[172:175], v[24:27]
	v_mfma_f32_16x16x32_bf16 v[20:23], v[116:119], v[176:179], v[20:23]
	v_mfma_f32_16x16x32_bf16 v[24:27], v[120:123], v[164:167], v[24:27]
	v_mfma_f32_16x16x32_bf16 v[20:23], v[120:123], v[168:171], v[20:23]
	v_mfma_f32_16x16x32_bf16 v[8:11], v[124:127], v[172:175], v[8:11]
	v_mfma_f32_16x16x32_bf16 v[4:7], v[124:127], v[176:179], v[4:7]
	v_mfma_f32_16x16x32_bf16 v[8:11], v[128:131], v[164:167], v[8:11]
	v_mfma_f32_16x16x32_bf16 v[4:7], v[128:131], v[168:171], v[4:7]
	s_sub_u32 s24, s24, 1
	s_cmp_lg_u32 s24, 0
	s_cbranch_scc1 .Lconv_seg4
	s_waitcnt lgkmcnt(0)
	v_mfma_f32_16x16x32_bf16 v[48:51], v[140:143], v[180:183], v[48:51]
	v_add_u32_e32 v95, -1, v95
	v_add_u32_e32 v73, 0xffffffe0, v95
	v_mfma_f32_16x16x32_bf16 v[44:47], v[140:143], v[184:187], v[44:47]
	v_cmp_gt_u32_e64 s[4:5], 64, v73
	v_add_u32_e32 v74, 0xfffffff0, v95
	v_mfma_f32_16x16x32_bf16 v[48:51], v[144:147], v[172:175], v[48:51]
	v_cmp_gt_u32_e64 s[6:7], 64, v74
	v_cmp_gt_u32_e64 s[20:21], 64, v95
	v_mfma_f32_16x16x32_bf16 v[44:47], v[144:147], v[176:179], v[44:47]
	v_add_u32_e32 v97, 0xffffff80, v97
	ds_read2_b32 v[164:165], v97 offset0:24 offset1:25
	v_mfma_f32_16x16x32_bf16 v[32:35], v[148:151], v[180:183], v[32:35]
	ds_read2_b32 v[166:167], v97 offset0:26 offset1:27
	ds_read2_b32 v[168:169], v97 offset0:16 offset1:17
	v_mfma_f32_16x16x32_bf16 v[28:31], v[148:151], v[184:187], v[28:31]
	ds_read2_b32 v[170:171], v97 offset0:18 offset1:19
	v_add_u32_e32 v96, 0xffffff60, v96
	v_mfma_f32_16x16x32_bf16 v[32:35], v[152:155], v[172:175], v[32:35]
	v_cndmask_b32_e64 v77, v69, v96, s[4:5]
	ds_read_b128 v[108:111], v77 offset:2560
	v_mfma_f32_16x16x32_bf16 v[28:31], v[152:155], v[176:179], v[28:31]
	ds_read_b128 v[112:115], v77 offset:2624
	v_cndmask_b32_e64 v78, v70, v96, s[6:7]
	v_mfma_f32_16x16x32_bf16 v[16:19], v[156:159], v[180:183], v[16:19]
	ds_read_b128 v[116:119], v78 offset:5120
	ds_read_b128 v[120:123], v78 offset:5184
	v_mfma_f32_16x16x32_bf16 v[12:15], v[156:159], v[184:187], v[12:15]
	v_cndmask_b32_e64 v79, v71, v96, s[20:21]
	ds_read_b128 v[124:127], v79 offset:7680
	v_mfma_f32_16x16x32_bf16 v[16:19], v[160:163], v[172:175], v[16:19]
	ds_read_b128 v[128:131], v79 offset:7744
	v_mfma_f32_16x16x32_bf16 v[12:15], v[160:163], v[176:179], v[12:15]
	ds_read2_b32 v[172:173], v97 offset0:8 offset1:9
	ds_read2_b32 v[174:175], v97 offset0:10 offset1:11
	v_mfma_f32_16x16x32_bf16 v[40:43], v[140:143], v[188:191], v[40:43]
	ds_read2_b32 v[176:177], v97 offset0:0 offset1:1
	ds_read2_b32 v[178:179], v97 offset0:2 offset1:3
	v_mfma_f32_16x16x32_bf16 v[36:39], v[140:143], v[192:195], v[36:39]
	v_mfma_f32_16x16x32_bf16 v[40:43], v[144:147], v[180:183], v[40:43]
	v_mfma_f32_16x16x32_bf16 v[36:39], v[144:147], v[184:187], v[36:39]
	v_mfma_f32_16x16x32_bf16 v[24:27], v[148:151], v[188:191], v[24:27]
	v_mfma_f32_16x16x32_bf16 v[20:23], v[148:151], v[192:195], v[20:23]
	v_mfma_f32_16x16x32_bf16 v[24:27], v[152:155], v[180:183], v[24:27]
	v_mfma_f32_16x16x32_bf16 v[20:23], v[152:155], v[184:187], v[20:23]
	v_mfma_f32_16x16x32_bf16 v[8:11], v[156:159], v[188:191], v[8:11]
	v_mfma_f32_16x16x32_bf16 v[4:7], v[156:159], v[192:195], v[4:7]
	v_mfma_f32_16x16x32_bf16 v[8:11], v[160:163], v[180:183], v[8:11]
	v_mfma_f32_16x16x32_bf16 v[4:7], v[160:163], v[184:187], v[4:7]
	s_waitcnt lgkmcnt(0)
; #define MFMA16(a, b, c) __builtin_amdgcn_mfma_f32_16x16x32_bf16(__builtin_bit_cast(bf16x8, (a)), __builtin_bit_cast(bf16x8, (b)), (c), 0, 0, 0)
; DI void hyena_conv_unit(const Params& p, int item, char* smem) {
;     ...
;   for (int d = -63; d <= 63; ++d) {
; #pragma unroll
;     for (int kk = 0; kk < 2; ++kk) {
;       u32x4 bfr[4];
; #pragma unroll
;       for (int nn = 0; nn < 4; ++nn) bfr[nn] = bfrag(4 * d + nn - 2 * kk);
; #pragma unroll
;       for (int rb = 0; rb < 4; ++rb) {
;         if (d >= 16 * rb - 63 && d <= 16 * rb + 15) {
;           int t1 = 16 * rb + n, s1 = t1 - d;
;           u32x4 a = zero4();
;           if (s1 >= 0 && s1 < 64) a = *(const u32x4*)(su + s1 * 72 + 32 * kk + 8 * g);
; #pragma unroll
;           for (int nn = 0; nn < 4; ++nn) acc[rb][nn] = MFMA16(a, bfr[nn], acc[rb][nn]);
;         }
;       }
;     }
;   }
	v_mfma_f32_16x16x32_bf16 v[48:51], v[108:111], v[164:167], v[48:51]
	v_add_u32_e32 v95, -1, v95
	v_add_u32_e32 v74, 0xfffffff0, v95
	v_mfma_f32_16x16x32_bf16 v[44:47], v[108:111], v[168:171], v[44:47]
	v_cmp_gt_u32_e64 s[6:7], 64, v74
	v_cmp_gt_u32_e64 s[20:21], 64, v95
	v_mfma_f32_16x16x32_bf16 v[48:51], v[112:115], v[188:191], v[48:51]
	v_add_u32_e32 v97, 0xffffff80, v97
	ds_read2_b32 v[180:181], v97 offset0:24 offset1:25
	v_mfma_f32_16x16x32_bf16 v[44:47], v[112:115], v[192:195], v[44:47]
	ds_read2_b32 v[182:183], v97 offset0:26 offset1:27
	ds_read2_b32 v[184:185], v97 offset0:16 offset1:17
	v_mfma_f32_16x16x32_bf16 v[32:35], v[116:119], v[164:167], v[32:35]
	ds_read2_b32 v[186:187], v97 offset0:18 offset1:19
	v_add_u32_e32 v96, 0xffffff60, v96
	v_mfma_f32_16x16x32_bf16 v[28:31], v[116:119], v[168:171], v[28:31]
	v_cndmask_b32_e64 v78, v70, v96, s[6:7]
	ds_read_b128 v[148:151], v78 offset:5120
	v_mfma_f32_16x16x32_bf16 v[32:35], v[120:123], v[188:191], v[32:35]
	ds_read_b128 v[152:155], v78 offset:5184
	v_cndmask_b32_e64 v79, v71, v96, s[20:21]
	v_mfma_f32_16x16x32_bf16 v[28:31], v[120:123], v[192:195], v[28:31]
	ds_read_b128 v[156:159], v79 offset:7680
	ds_read_b128 v[160:163], v79 offset:7744
	v_mfma_f32_16x16x32_bf16 v[16:19], v[124:127], v[164:167], v[16:19]
	v_mfma_f32_16x16x32_bf16 v[12:15], v[124:127], v[168:171], v[12:15]
	v_mfma_f32_16x16x32_bf16 v[16:19], v[128:131], v[188:191], v[16:19]
	v_mfma_f32_16x16x32_bf16 v[12:15], v[128:131], v[192:195], v[12:15]
	ds_read2_b32 v[188:189], v97 offset0:8 offset1:9
	ds_read2_b32 v[190:191], v97 offset0:10 offset1:11
	v_mfma_f32_16x16x32_bf16 v[40:43], v[108:111], v[172:175], v[40:43]
	ds_read2_b32 v[192:193], v97 offset0:0 offset1:1
	ds_read2_b32 v[194:195], v97 offset0:2 offset1:3
	v_mfma_f32_16x16x32_bf16 v[36:39], v[108:111], v[176:179], v[36:39]
	v_mfma_f32_16x16x32_bf16 v[40:43], v[112:115], v[164:167], v[40:43]
	v_mfma_f32_16x16x32_bf16 v[36:39], v[112:115], v[168:171], v[36:39]
	v_mfma_f32_16x16x32_bf16 v[24:27], v[116:119], v[172:175], v[24:27]
	v_mfma_f32_16x16x32_bf16 v[20:23], v[116:119], v[176:179], v[20:23]
	v_mfma_f32_16x16x32_bf16 v[24:27], v[120:123], v[164:167], v[24:27]
	v_mfma_f32_16x16x32_bf16 v[20:23], v[120:123], v[168:171], v[20:23]
	v_mfma_f32_16x16x32_bf16 v[8:11], v[124:127], v[172:175], v[8:11]
	v_mfma_f32_16x16x32_bf16 v[4:7], v[124:127], v[176:179], v[4:7]
	v_mfma_f32_16x16x32_bf16 v[8:11], v[128:131], v[164:167], v[8:11]
	v_mfma_f32_16x16x32_bf16 v[4:7], v[128:131], v[168:171], v[4:7]
	s_mov_b32 s24, 7
.Lconv_seg5:
	s_waitcnt lgkmcnt(0)
	v_mfma_f32_16x16x32_bf16 v[32:35], v[148:151], v[180:183], v[32:35]
	v_add_u32_e32 v95, -1, v95
	v_add_u32_e32 v74, 0xfffffff0, v95
	v_mfma_f32_16x16x32_bf16 v[28:31], v[148:151], v[184:187], v[28:31]
	v_cmp_gt_u32_e64 s[6:7], 64, v74
	v_cmp_gt_u32_e64 s[20:21], 64, v95
	v_mfma_f32_16x16x32_bf16 v[32:35], v[152:155], v[172:175], v[32:35]
	v_add_u32_e32 v97, 0xffffff80, v97
	ds_read2_b32 v[164:165], v97 offset0:24 offset1:25
	v_mfma_f32_16x16x32_bf16 v[28:31], v[152:155], v[176:179], v[28:31]
	ds_read2_b32 v[166:167], v97 offset0:26 offset1:27
	ds_read2_b32 v[168:169], v97 offset0:16 offset1:17
	v_mfma_f32_16x16x32_bf16 v[16:19], v[156:159], v[180:183], v[16:19]
	ds_read2_b32 v[170:171], v97 offset0:18 offset1:19
	v_add_u32_e32 v96, 0xffffff60, v96
	v_mfma_f32_16x16x32_bf16 v[12:15], v[156:159], v[184:187], v[12:15]
	v_cndmask_b32_e64 v78, v70, v96, s[6:7]
	ds_read_b128 v[116:119], v78 offset:5120
	v_mfma_f32_16x16x32_bf16 v[16:19], v[160:163], v[172:175], v[16:19]
	ds_read_b128 v[120:123], v78 offset:5184
	v_cndmask_b32_e64 v79, v71, v96, s[20:21]
	v_mfma_f32_16x16x32_bf16 v[12:15], v[160:163], v[176:179], v[12:15]
	ds_read_b128 v[124:127], v79 offset:7680
	ds_read_b128 v[128:131], v79 offset:7744
	v_mfma_f32_16x16x32_bf16 v[24:27], v[148:151], v[188:191], v[24:27]
	ds_read2_b32 v[172:173], v97 offset0:8 offset1:9
	ds_read2_b32 v[174:175], v97 offset0:10 offset1:11
	v_mfma_f32_16x16x32_bf16 v[20:23], v[148:151], v[192:195], v[20:23]
	ds_read2_b32 v[176:177], v97 offset0:0 offset1:1
	ds_read2_b32 v[178:179], v97 offset0:2 offset1:3
	v_mfma_f32_16x16x32_bf16 v[24:27], v[152:155], v[180:183], v[24:27]
	v_mfma_f32_16x16x32_bf16 v[20:23], v[152:155], v[184:187], v[20:23]
	v_mfma_f32_16x16x32_bf16 v[8:11], v[156:159], v[188:191], v[8:11]
	v_mfma_f32_16x16x32_bf16 v[4:7], v[156:159], v[192:195], v[4:7]
	v_mfma_f32_16x16x32_bf16 v[8:11], v[160:163], v[180:183], v[8:11]
	v_mfma_f32_16x16x32_bf16 v[4:7], v[160:163], v[184:187], v[4:7]
	s_waitcnt lgkmcnt(0)
	v_mfma_f32_16x16x32_bf16 v[32:35], v[116:119], v[164:167], v[32:35]
	v_add_u32_e32 v95, -1, v95
	v_add_u32_e32 v74, 0xfffffff0, v95
	v_mfma_f32_16x16x32_bf16 v[28:31], v[116:119], v[168:171], v[28:31]
	v_cmp_gt_u32_e64 s[6:7], 64, v74
	v_cmp_gt_u32_e64 s[20:21], 64, v95
	v_mfma_f32_16x16x32_bf16 v[32:35], v[120:123], v[188:191], v[32:35]
	v_add_u32_e32 v97, 0xffffff80, v97
	ds_read2_b32 v[180:181], v97 offset0:24 offset1:25
	v_mfma_f32_16x16x32_bf16 v[28:31], v[120:123], v[192:195], v[28:31]
	ds_read2_b32 v[182:183], v97 offset0:26 offset1:27
	ds_read2_b32 v[184:185], v97 offset0:16 offset1:17
	v_mfma_f32_16x16x32_bf16 v[16:19], v[124:127], v[164:167], v[16:19]
	ds_read2_b32 v[186:187], v97 offset0:18 offset1:19
	v_add_u32_e32 v96, 0xffffff60, v96
	v_mfma_f32_16x16x32_bf16 v[12:15], v[124:127], v[168:171], v[12:15]
	v_cndmask_b32_e64 v78, v70, v96, s[6:7]
	ds_read_b128 v[148:151], v78 offset:5120
	v_mfma_f32_16x16x32_bf16 v[16:19], v[128:131], v[188:191], v[16:19]
	ds_read_b128 v[152:155], v78 offset:5184
	v_cndmask_b32_e64 v79, v71, v96, s[20:21]
	v_mfma_f32_16x16x32_bf16 v[12:15], v[128:131], v[192:195], v[12:15]
	ds_read_b128 v[156:159], v79 offset:7680
	ds_read_b128 v[160:163], v79 offset:7744
	v_mfma_f32_16x16x32_bf16 v[24:27], v[116:119], v[172:175], v[24:27]
	ds_read2_b32 v[188:189], v97 offset0:8 offset1:9
	ds_read2_b32 v[190:191], v97 offset0:10 offset1:11
	v_mfma_f32_16x16x32_bf16 v[20:23], v[116:119], v[176:179], v[20:23]
	ds_read2_b32 v[192:193], v97 offset0:0 offset1:1
	ds_read2_b32 v[194:195], v97 offset0:2 offset1:3
	v_mfma_f32_16x16x32_bf16 v[24:27], v[120:123], v[164:167], v[24:27]
	v_mfma_f32_16x16x32_bf16 v[20:23], v[120:123], v[168:171], v[20:23]
	v_mfma_f32_16x16x32_bf16 v[8:11], v[124:127], v[172:175], v[8:11]
	v_mfma_f32_16x16x32_bf16 v[4:7], v[124:127], v[176:179], v[4:7]
	v_mfma_f32_16x16x32_bf16 v[8:11], v[128:131], v[164:167], v[8:11]
	v_mfma_f32_16x16x32_bf16 v[4:7], v[128:131], v[168:171], v[4:7]
	s_sub_u32 s24, s24, 1
	s_cmp_lg_u32 s24, 0
	s_cbranch_scc1 .Lconv_seg5
; #define MFMA16(a, b, c) __builtin_amdgcn_mfma_f32_16x16x32_bf16(__builtin_bit_cast(bf16x8, (a)), __builtin_bit_cast(bf16x8, (b)), (c), 0, 0, 0)
; DI void hyena_conv_unit(const Params& p, int item, char* smem) {
;     ...
;   for (int d = -63; d <= 63; ++d) {
; #pragma unroll
;     for (int kk = 0; kk < 2; ++kk) {
;       u32x4 bfr[4];
; #pragma unroll
;       for (int nn = 0; nn < 4; ++nn) bfr[nn] = bfrag(4 * d + nn - 2 * kk);
; #pragma unroll
;       for (int rb = 0; rb < 4; ++rb) {
;         if (d >= 16 * rb - 63 && d <= 16 * rb + 15) {
;           int t1 = 16 * rb + n, s1 = t1 - d;
;           u32x4 a = zero4();
;           if (s1 >= 0 && s1 < 64) a = *(const u32x4*)(su + s1 * 72 + 32 * kk + 8 * g);
; #pragma unroll
;           for (int nn = 0; nn < 4; ++nn) acc[rb][nn] = MFMA16(a, bfr[nn], acc[rb][nn]);
;         }
;       }
;     }
;   }
	s_waitcnt lgkmcnt(0)
	v_mfma_f32_16x16x32_bf16 v[32:35], v[148:151], v[180:183], v[32:35]
	v_add_u32_e32 v95, -1, v95
	v_add_u32_e32 v74, 0xfffffff0, v95
	v_mfma_f32_16x16x32_bf16 v[28:31], v[148:151], v[184:187], v[28:31]
	v_cmp_gt_u32_e64 s[6:7], 64, v74
	v_cmp_gt_u32_e64 s[20:21], 64, v95
	v_mfma_f32_16x16x32_bf16 v[32:35], v[152:155], v[172:175], v[32:35]
	v_add_u32_e32 v97, 0xffffff80, v97
	ds_read2_b32 v[164:165], v97 offset0:24 offset1:25
	v_mfma_f32_16x16x32_bf16 v[28:31], v[152:155], v[176:179], v[28:31]
	ds_read2_b32 v[166:167], v97 offset0:26 offset1:27
	ds_read2_b32 v[168:169], v97 offset0:16 offset1:17
	v_mfma_f32_16x16x32_bf16 v[16:19], v[156:159], v[180:183], v[16:19]
	ds_read2_b32 v[170:171], v97 offset0:18 offset1:19
	v_add_u32_e32 v96, 0xffffff60, v96
	v_mfma_f32_16x16x32_bf16 v[12:15], v[156:159], v[184:187], v[12:15]
	v_cndmask_b32_e64 v78, v70, v96, s[6:7]
	ds_read_b128 v[116:119], v78 offset:5120
	v_mfma_f32_16x16x32_bf16 v[16:19], v[160:163], v[172:175], v[16:19]
	ds_read_b128 v[120:123], v78 offset:5184
	v_cndmask_b32_e64 v79, v71, v96, s[20:21]
	v_mfma_f32_16x16x32_bf16 v[12:15], v[160:163], v[176:179], v[12:15]
	ds_read_b128 v[124:127], v79 offset:7680
	ds_read_b128 v[128:131], v79 offset:7744
	v_mfma_f32_16x16x32_bf16 v[24:27], v[148:151], v[188:191], v[24:27]
	ds_read2_b32 v[172:173], v97 offset0:8 offset1:9
	ds_read2_b32 v[174:175], v97 offset0:10 offset1:11
	v_mfma_f32_16x16x32_bf16 v[20:23], v[148:151], v[192:195], v[20:23]
	ds_read2_b32 v[176:177], v97 offset0:0 offset1:1
	ds_read2_b32 v[178:179], v97 offset0:2 offset1:3
	v_mfma_f32_16x16x32_bf16 v[24:27], v[152:155], v[180:183], v[24:27]
	v_mfma_f32_16x16x32_bf16 v[20:23], v[152:155], v[184:187], v[20:23]
	v_mfma_f32_16x16x32_bf16 v[8:11], v[156:159], v[188:191], v[8:11]
	v_mfma_f32_16x16x32_bf16 v[4:7], v[156:159], v[192:195], v[4:7]
	v_mfma_f32_16x16x32_bf16 v[8:11], v[160:163], v[180:183], v[8:11]
	v_mfma_f32_16x16x32_bf16 v[4:7], v[160:163], v[184:187], v[4:7]
	s_waitcnt lgkmcnt(0)
	v_mfma_f32_16x16x32_bf16 v[32:35], v[116:119], v[164:167], v[32:35]
	v_add_u32_e32 v95, -1, v95
	v_cmp_gt_u32_e64 s[20:21], 64, v95
	v_mfma_f32_16x16x32_bf16 v[28:31], v[116:119], v[168:171], v[28:31]
	v_add_u32_e32 v97, 0xffffff80, v97
	ds_read2_b32 v[180:181], v97 offset0:24 offset1:25
	v_mfma_f32_16x16x32_bf16 v[32:35], v[120:123], v[188:191], v[32:35]
	ds_read2_b32 v[182:183], v97 offset0:26 offset1:27
	ds_read2_b32 v[184:185], v97 offset0:16 offset1:17
	v_mfma_f32_16x16x32_bf16 v[28:31], v[120:123], v[192:195], v[28:31]
	ds_read2_b32 v[186:187], v97 offset0:18 offset1:19
	v_add_u32_e32 v96, 0xffffff60, v96
	v_mfma_f32_16x16x32_bf16 v[16:19], v[124:127], v[164:167], v[16:19]
	v_cndmask_b32_e64 v79, v71, v96, s[20:21]
	ds_read_b128 v[156:159], v79 offset:7680
	v_mfma_f32_16x16x32_bf16 v[12:15], v[124:127], v[168:171], v[12:15]
	ds_read_b128 v[160:163], v79 offset:7744
	v_mfma_f32_16x16x32_bf16 v[16:19], v[128:131], v[188:191], v[16:19]
	v_mfma_f32_16x16x32_bf16 v[12:15], v[128:131], v[192:195], v[12:15]
	ds_read2_b32 v[188:189], v97 offset0:8 offset1:9
	ds_read2_b32 v[190:191], v97 offset0:10 offset1:11
	v_mfma_f32_16x16x32_bf16 v[24:27], v[116:119], v[172:175], v[24:27]
	ds_read2_b32 v[192:193], v97 offset0:0 offset1:1
	ds_read2_b32 v[194:195], v97 offset0:2 offset1:3
	v_mfma_f32_16x16x32_bf16 v[20:23], v[116:119], v[176:179], v[20:23]
	v_mfma_f32_16x16x32_bf16 v[24:27], v[120:123], v[164:167], v[24:27]
	v_mfma_f32_16x16x32_bf16 v[20:23], v[120:123], v[168:171], v[20:23]
	v_mfma_f32_16x16x32_bf16 v[8:11], v[124:127], v[172:175], v[8:11]
	v_mfma_f32_16x16x32_bf16 v[4:7], v[124:127], v[176:179], v[4:7]
	v_mfma_f32_16x16x32_bf16 v[8:11], v[128:131], v[164:167], v[8:11]
	v_mfma_f32_16x16x32_bf16 v[4:7], v[128:131], v[168:171], v[4:7]
	s_mov_b32 s24, 6
; #define MFMA16(a, b, c) __builtin_amdgcn_mfma_f32_16x16x32_bf16(__builtin_bit_cast(bf16x8, (a)), __builtin_bit_cast(bf16x8, (b)), (c), 0, 0, 0)
; DI void hyena_conv_unit(const Params& p, int item, char* smem) {
;     ...
;   for (int d = -63; d <= 63; ++d) {
; #pragma unroll
;     for (int kk = 0; kk < 2; ++kk) {
;       u32x4 bfr[4];
; #pragma unroll
;       for (int nn = 0; nn < 4; ++nn) bfr[nn] = bfrag(4 * d + nn - 2 * kk);
; #pragma unroll
;       for (int rb = 0; rb < 4; ++rb) {
;         if (d >= 16 * rb - 63 && d <= 16 * rb + 15) {
;           int t1 = 16 * rb + n, s1 = t1 - d;
;           u32x4 a = zero4();
;           if (s1 >= 0 && s1 < 64) a = *(const u32x4*)(su + s1 * 72 + 32 * kk + 8 * g);
; #pragma unroll
;           for (int nn = 0; nn < 4; ++nn) acc[rb][nn] = MFMA16(a, bfr[nn], acc[rb][nn]);
;         }
;       }
;     }
;   }
.Lconv_seg6:
	s_waitcnt lgkmcnt(0)
	v_mfma_f32_16x16x32_bf16 v[16:19], v[156:159], v[180:183], v[16:19]
	v_add_u32_e32 v95, -1, v95
	v_cmp_gt_u32_e64 s[20:21], 64, v95
	v_add_u32_e32 v97, 0xffffff80, v97
	v_mfma_f32_16x16x32_bf16 v[12:15], v[156:159], v[184:187], v[12:15]
	ds_read2_b32 v[164:165], v97 offset0:24 offset1:25
	ds_read2_b32 v[166:167], v97 offset0:26 offset1:27
	ds_read2_b32 v[168:169], v97 offset0:16 offset1:17
	v_mfma_f32_16x16x32_bf16 v[16:19], v[160:163], v[172:175], v[16:19]
	ds_read2_b32 v[170:171], v97 offset0:18 offset1:19
	v_add_u32_e32 v96, 0xffffff60, v96
	v_cndmask_b32_e64 v79, v71, v96, s[20:21]
	v_mfma_f32_16x16x32_bf16 v[12:15], v[160:163], v[176:179], v[12:15]
	ds_read_b128 v[124:127], v79 offset:7680
	ds_read_b128 v[128:131], v79 offset:7744
	ds_read2_b32 v[172:173], v97 offset0:8 offset1:9
	v_mfma_f32_16x16x32_bf16 v[8:11], v[156:159], v[188:191], v[8:11]
	ds_read2_b32 v[174:175], v97 offset0:10 offset1:11
	ds_read2_b32 v[176:177], v97 offset0:0 offset1:1
	ds_read2_b32 v[178:179], v97 offset0:2 offset1:3
	v_mfma_f32_16x16x32_bf16 v[4:7], v[156:159], v[192:195], v[4:7]
	v_mfma_f32_16x16x32_bf16 v[8:11], v[160:163], v[180:183], v[8:11]
	v_mfma_f32_16x16x32_bf16 v[4:7], v[160:163], v[184:187], v[4:7]
	s_waitcnt lgkmcnt(0)
	v_mfma_f32_16x16x32_bf16 v[16:19], v[124:127], v[164:167], v[16:19]
	v_add_u32_e32 v95, -1, v95
	v_cmp_gt_u32_e64 s[20:21], 64, v95
	v_add_u32_e32 v97, 0xffffff80, v97
	v_mfma_f32_16x16x32_bf16 v[12:15], v[124:127], v[168:171], v[12:15]
	ds_read2_b32 v[180:181], v97 offset0:24 offset1:25
	ds_read2_b32 v[182:183], v97 offset0:26 offset1:27
	ds_read2_b32 v[184:185], v97 offset0:16 offset1:17
	v_mfma_f32_16x16x32_bf16 v[16:19], v[128:131], v[188:191], v[16:19]
	ds_read2_b32 v[186:187], v97 offset0:18 offset1:19
	v_add_u32_e32 v96, 0xffffff60, v96
	v_cndmask_b32_e64 v79, v71, v96, s[20:21]
	v_mfma_f32_16x16x32_bf16 v[12:15], v[128:131], v[192:195], v[12:15]
	ds_read_b128 v[156:159], v79 offset:7680
	ds_read_b128 v[160:163], v79 offset:7744
	ds_read2_b32 v[188:189], v97 offset0:8 offset1:9
	v_mfma_f32_16x16x32_bf16 v[8:11], v[124:127], v[172:175], v[8:11]
	ds_read2_b32 v[190:191], v97 offset0:10 offset1:11
	ds_read2_b32 v[192:193], v97 offset0:0 offset1:1
	ds_read2_b32 v[194:195], v97 offset0:2 offset1:3
	v_mfma_f32_16x16x32_bf16 v[4:7], v[124:127], v[176:179], v[4:7]
	v_mfma_f32_16x16x32_bf16 v[8:11], v[128:131], v[164:167], v[8:11]
	v_mfma_f32_16x16x32_bf16 v[4:7], v[128:131], v[168:171], v[4:7]
	s_sub_u32 s24, s24, 1
	s_cmp_lg_u32 s24, 0
	s_cbranch_scc1 .Lconv_seg6
	s_waitcnt lgkmcnt(0)
	v_mfma_f32_16x16x32_bf16 v[16:19], v[156:159], v[180:183], v[16:19]
	v_add_u32_e32 v95, -1, v95
	v_cmp_gt_u32_e64 s[20:21], 64, v95
	v_add_u32_e32 v97, 0xffffff80, v97
	v_mfma_f32_16x16x32_bf16 v[12:15], v[156:159], v[184:187], v[12:15]
	ds_read2_b32 v[164:165], v97 offset0:24 offset1:25
	ds_read2_b32 v[166:167], v97 offset0:26 offset1:27
	ds_read2_b32 v[168:169], v97 offset0:16 offset1:17
	v_mfma_f32_16x16x32_bf16 v[16:19], v[160:163], v[172:175], v[16:19]
	ds_read2_b32 v[170:171], v97 offset0:18 offset1:19
	v_add_u32_e32 v96, 0xffffff60, v96
	v_cndmask_b32_e64 v79, v71, v96, s[20:21]
	v_mfma_f32_16x16x32_bf16 v[12:15], v[160:163], v[176:179], v[12:15]
	ds_read_b128 v[124:127], v79 offset:7680
	ds_read_b128 v[128:131], v79 offset:7744
	ds_read2_b32 v[172:173], v97 offset0:8 offset1:9
	v_mfma_f32_16x16x32_bf16 v[8:11], v[156:159], v[188:191], v[8:11]
	ds_read2_b32 v[174:175], v97 offset0:10 offset1:11
	ds_read2_b32 v[176:177], v97 offset0:0 offset1:1
	ds_read2_b32 v[178:179], v97 offset0:2 offset1:3
	v_mfma_f32_16x16x32_bf16 v[4:7], v[156:159], v[192:195], v[4:7]
	v_mfma_f32_16x16x32_bf16 v[8:11], v[160:163], v[180:183], v[8:11]
	v_mfma_f32_16x16x32_bf16 v[4:7], v[160:163], v[184:187], v[4:7]
	s_waitcnt lgkmcnt(0)
	v_mfma_f32_16x16x32_bf16 v[16:19], v[124:127], v[164:167], v[16:19]
	v_add_u32_e32 v95, -1, v95
	v_cmp_gt_u32_e64 s[20:21], 64, v95
	v_add_u32_e32 v97, 0xffffff80, v97
	v_mfma_f32_16x16x32_bf16 v[12:15], v[124:127], v[168:171], v[12:15]
	ds_read2_b32 v[180:181], v97 offset0:24 offset1:25
	ds_read2_b32 v[182:183], v97 offset0:26 offset1:27
	ds_read2_b32 v[184:185], v97 offset0:16 offset1:17
	v_mfma_f32_16x16x32_bf16 v[16:19], v[128:131], v[188:191], v[16:19]
	ds_read2_b32 v[186:187], v97 offset0:18 offset1:19
	v_add_u32_e32 v96, 0xffffff60, v96
	v_cndmask_b32_e64 v79, v71, v96, s[20:21]
	v_mfma_f32_16x16x32_bf16 v[12:15], v[128:131], v[192:195], v[12:15]
	ds_read_b128 v[156:159], v79 offset:7680
	ds_read_b128 v[160:163], v79 offset:7744
	ds_read2_b32 v[188:189], v97 offset0:8 offset1:9
	v_mfma_f32_16x16x32_bf16 v[8:11], v[124:127], v[172:175], v[8:11]
	ds_read2_b32 v[190:191], v97 offset0:10 offset1:11
	ds_read2_b32 v[192:193], v97 offset0:0 offset1:1
	ds_read2_b32 v[194:195], v97 offset0:2 offset1:3
	v_mfma_f32_16x16x32_bf16 v[4:7], v[124:127], v[176:179], v[4:7]
	v_mfma_f32_16x16x32_bf16 v[8:11], v[128:131], v[164:167], v[8:11]
	v_mfma_f32_16x16x32_bf16 v[4:7], v[128:131], v[168:171], v[4:7]
	s_waitcnt lgkmcnt(0)
	v_mfma_f32_16x16x32_bf16 v[16:19], v[156:159], v[180:183], v[16:19]
	v_mfma_f32_16x16x32_bf16 v[12:15], v[156:159], v[184:187], v[12:15]
	v_mfma_f32_16x16x32_bf16 v[16:19], v[160:163], v[172:175], v[16:19]
	v_mfma_f32_16x16x32_bf16 v[12:15], v[160:163], v[176:179], v[12:15]
	v_mfma_f32_16x16x32_bf16 v[8:11], v[156:159], v[188:191], v[8:11]
	v_mfma_f32_16x16x32_bf16 v[4:7], v[156:159], v[192:195], v[4:7]
	v_mfma_f32_16x16x32_bf16 v[8:11], v[160:163], v[180:183], v[8:11]
	v_mfma_f32_16x16x32_bf16 v[4:7], v[160:163], v[184:187], v[4:7]
	s_nop 7
	s_nop 3
	s_branch .LBB0_896
